# out-proj fused: SSD-half GEMM first, accumulators scaled by rsqrt(ssq/1024+eps) in registers and carried into the GLA-half K-loop, single residual epilogue (saves one f32 read+write pass); LN10 keeps
# speedup vs baseline: 1.0569x; 1.0236x over previous
_Z4mega6Params:
	s_load_dwordx16 s[48:63], s[0:1], 0x100
	s_load_dword s36, s[0:1], 0x150
	s_load_dwordx2 s[96:97], s[0:1], 0x148
	s_mov_b32 s30, s2
	s_add_u32 s2, s0, 0x148
	s_addc_u32 s3, s1, 0
	v_cmp_gt_u32_e32 vcc, 2, v0
	s_and_saveexec_b64 s[4:5], vcc
	v_lshl_add_u32 v1, v0, 2, 0
	v_add_u32_e32 v1, 0x20000, v1
	v_mov_b32_e32 v2, 0
	ds_write_b32 v1, v2
	s_or_b64 exec, exec, s[4:5]
	s_load_dwordx16 s[64:79], s[0:1], 0x0
	s_waitcnt lgkmcnt(0)
	s_barrier
	v_writelane_b32 v255, s64, 42
	v_writelane_b32 v255, s65, 43
	v_writelane_b32 v255, s48, 40
	v_writelane_b32 v255, s49, 41
	s_add_u32 s34, s62, 0xf71a000
	s_getreg_b32 s4, hwreg(HW_REG_XCC_ID, 0, 4)
	s_addc_u32 s35, s63, 0
	s_and_b32 s37, s4, 15
	v_cmp_eq_u32_e64 s[38:39], 0, v0
	s_and_saveexec_b64 s[4:5], s[38:39]
	s_cbranch_execz .LBB0_5
	s_mov_b64 s[6:7], exec
	v_mbcnt_lo_u32_b32 v1, s6, 0
	v_mbcnt_hi_u32_b32 v1, s7, v1
	v_cmp_eq_u32_e32 vcc, 0, v1
	s_and_b64 s[8:9], exec, vcc
	s_mov_b64 exec, s[8:9]
	s_cbranch_execz .LBB0_5
	s_lshl_b32 s8, s37, 8
	s_bcnt1_i32_b64 s6, s[6:7]
	v_mov_b32_e32 v1, s8
	v_mov_b32_e32 v2, s6
	global_atomic_add v1, v2, s[34:35] offset:1024

.LBB0_780:
	s_movk_i32 s6, 0x7ff
	v_cmp_lt_i32_e32 vcc, s6, v66
	s_and_saveexec_b64 s[6:7], vcc
	s_xor_b64 s[6:7], exec, s[6:7]
	s_cbranch_execz .LBB0_782
	s_movk_i32 s11, 0x80
	v_add_u32_e32 v2, 0xfffff800, v66
	v_bfe_u32 v86, v66, 1, 2
	v_and_or_b32 v67, v77, s11, v1
	v_lshrrev_b32_e32 v87, 3, v2
	v_lshlrev_b32_e32 v2, 6, v67
	v_lshlrev_b32_e32 v3, 14, v86
	v_or3_b32 v89, v3, v2, v68
	v_lshlrev_b32_e32 v90, 4, v87
	v_lshl_or_b32 v88, v86, 13, v68
	v_add_u32_e32 v70, v89, v90
	v_lshlrev_b64 v[2:3], 9, v[70:71]
	v_add_u32_e32 v70, v88, v90
	v_lshlrev_b64 v[6:7], 9, v[70:71]
	v_lshl_add_u64 v[2:3], v[72:73], 0, v[2:3]
	v_lshl_add_u64 v[6:7], v[74:75], 0, v[6:7]
	s_mov_b64 vcc, 0x1000
	v_lshl_add_u64 v[100:101], v[2:3], 0, vcc
	s_mov_b64 vcc, 0x1000
	v_lshl_add_u64 v[102:103], v[6:7], 0, vcc
	s_mov_b64 vcc, 0x101000
	v_lshl_add_u64 v[104:105], v[6:7], 0, vcc
	s_mov_b64 vcc, 0x201000
	v_lshl_add_u64 v[106:107], v[6:7], 0, vcc
	s_mov_b64 vcc, 0x301000
	v_lshl_add_u64 v[108:109], v[6:7], 0, vcc
	global_load_dwordx4 v[112:115], v[100:101], off offset:-4096
	global_load_dwordx4 v[116:119], v[100:101], off offset:-3072
	global_load_dwordx4 v[144:147], v[102:103], off offset:-4096
	global_load_dwordx4 v[148:151], v[104:105], off offset:-4096
	global_load_dwordx4 v[152:155], v[106:107], off offset:-4096
	global_load_dwordx4 v[156:159], v[108:109], off offset:-4096
	global_load_dwordx4 v[120:123], v[100:101], off offset:-2048
	global_load_dwordx4 v[124:127], v[100:101], off offset:-1024
	global_load_dwordx4 v[128:131], v[100:101], off
	global_load_dwordx4 v[132:135], v[100:101], off offset:1024
	global_load_dwordx4 v[136:139], v[100:101], off offset:2048
	global_load_dwordx4 v[140:143], v[100:101], off offset:3072
	global_load_dwordx4 v[160:163], v[102:103], off offset:-3072
	global_load_dwordx4 v[164:167], v[104:105], off offset:-3072
	global_load_dwordx4 v[168:171], v[106:107], off offset:-3072
	global_load_dwordx4 v[172:175], v[108:109], off offset:-3072
	global_load_dwordx4 v[176:179], v[102:103], off offset:-2048
	global_load_dwordx4 v[180:183], v[104:105], off offset:-2048
	global_load_dwordx4 v[184:187], v[106:107], off offset:-2048
	global_load_dwordx4 v[188:191], v[108:109], off offset:-2048
	s_waitcnt vmcnt(17)
	v_mfma_f32_32x32x16_bf16 v[50:65], v[144:147], v[112:115], 0
	global_load_dwordx4 v[144:147], v[102:103], off offset:-1024
	s_waitcnt vmcnt(17)
	v_mfma_f32_32x32x16_bf16 v[34:49], v[148:151], v[112:115], 0
	global_load_dwordx4 v[148:151], v[104:105], off offset:-1024
	s_waitcnt vmcnt(17)
	v_mfma_f32_32x32x16_bf16 v[18:33], v[152:155], v[112:115], 0
	global_load_dwordx4 v[152:155], v[106:107], off offset:-1024
	s_waitcnt vmcnt(17)
	v_mfma_f32_32x32x16_bf16 v[2:17], v[156:159], v[112:115], 0
	global_load_dwordx4 v[156:159], v[108:109], off offset:-1024
	s_waitcnt vmcnt(11)
	v_mfma_f32_32x32x16_bf16 v[50:65], v[160:163], v[116:119], v[50:65]
	global_load_dwordx4 v[160:163], v[102:103], off
	s_waitcnt vmcnt(11)
	v_mfma_f32_32x32x16_bf16 v[34:49], v[164:167], v[116:119], v[34:49]
	global_load_dwordx4 v[164:167], v[104:105], off
	s_waitcnt vmcnt(11)
	v_mfma_f32_32x32x16_bf16 v[18:33], v[168:171], v[116:119], v[18:33]
	global_load_dwordx4 v[168:171], v[106:107], off
	s_waitcnt vmcnt(11)
	v_mfma_f32_32x32x16_bf16 v[2:17], v[172:175], v[116:119], v[2:17]
	global_load_dwordx4 v[172:175], v[108:109], off
	s_waitcnt vmcnt(11)
	v_mfma_f32_32x32x16_bf16 v[50:65], v[176:179], v[120:123], v[50:65]
	global_load_dwordx4 v[176:179], v[102:103], off offset:1024
	s_waitcnt vmcnt(11)
	v_mfma_f32_32x32x16_bf16 v[34:49], v[180:183], v[120:123], v[34:49]
	global_load_dwordx4 v[180:183], v[104:105], off offset:1024
	s_waitcnt vmcnt(11)
	v_mfma_f32_32x32x16_bf16 v[18:33], v[184:187], v[120:123], v[18:33]
	global_load_dwordx4 v[184:187], v[106:107], off offset:1024
	s_waitcnt vmcnt(11)
	v_mfma_f32_32x32x16_bf16 v[2:17], v[188:191], v[120:123], v[2:17]
	global_load_dwordx4 v[188:191], v[108:109], off offset:1024
	s_waitcnt vmcnt(11)
	v_mfma_f32_32x32x16_bf16 v[50:65], v[144:147], v[124:127], v[50:65]
	global_load_dwordx4 v[144:147], v[102:103], off offset:2048
	s_waitcnt vmcnt(11)
	v_mfma_f32_32x32x16_bf16 v[34:49], v[148:151], v[124:127], v[34:49]
	global_load_dwordx4 v[148:151], v[104:105], off offset:2048
	s_waitcnt vmcnt(11)
	v_mfma_f32_32x32x16_bf16 v[18:33], v[152:155], v[124:127], v[18:33]
	global_load_dwordx4 v[152:155], v[106:107], off offset:2048
	s_waitcnt vmcnt(11)
	v_mfma_f32_32x32x16_bf16 v[2:17], v[156:159], v[124:127], v[2:17]
	global_load_dwordx4 v[156:159], v[108:109], off offset:2048
	s_waitcnt vmcnt(11)
	v_mfma_f32_32x32x16_bf16 v[50:65], v[160:163], v[128:131], v[50:65]
	global_load_dwordx4 v[160:163], v[102:103], off offset:3072
	s_waitcnt vmcnt(11)
	v_mfma_f32_32x32x16_bf16 v[34:49], v[164:167], v[128:131], v[34:49]
	global_load_dwordx4 v[164:167], v[104:105], off offset:3072
	s_waitcnt vmcnt(11)
	v_mfma_f32_32x32x16_bf16 v[18:33], v[168:171], v[128:131], v[18:33]
	global_load_dwordx4 v[168:171], v[106:107], off offset:3072
	s_waitcnt vmcnt(11)
	v_mfma_f32_32x32x16_bf16 v[2:17], v[172:175], v[128:131], v[2:17]
	global_load_dwordx4 v[172:175], v[108:109], off offset:3072
	s_waitcnt vmcnt(11)
	v_mfma_f32_32x32x16_bf16 v[50:65], v[176:179], v[132:135], v[50:65]
	s_waitcnt vmcnt(10)
	v_mfma_f32_32x32x16_bf16 v[34:49], v[180:183], v[132:135], v[34:49]
	s_waitcnt vmcnt(9)
	v_mfma_f32_32x32x16_bf16 v[18:33], v[184:187], v[132:135], v[18:33]
	s_waitcnt vmcnt(8)
	v_mfma_f32_32x32x16_bf16 v[2:17], v[188:191], v[132:135], v[2:17]
	s_waitcnt vmcnt(7)
	v_mfma_f32_32x32x16_bf16 v[50:65], v[144:147], v[136:139], v[50:65]
	s_waitcnt vmcnt(6)
	v_mfma_f32_32x32x16_bf16 v[34:49], v[148:151], v[136:139], v[34:49]
	s_waitcnt vmcnt(5)
	v_mfma_f32_32x32x16_bf16 v[18:33], v[152:155], v[136:139], v[18:33]
	s_waitcnt vmcnt(4)
	v_mfma_f32_32x32x16_bf16 v[2:17], v[156:159], v[136:139], v[2:17]
	s_waitcnt vmcnt(3)
	v_mfma_f32_32x32x16_bf16 v[50:65], v[160:163], v[140:143], v[50:65]
	s_waitcnt vmcnt(2)
	v_mfma_f32_32x32x16_bf16 v[34:49], v[164:167], v[140:143], v[34:49]
	s_waitcnt vmcnt(1)
	v_mfma_f32_32x32x16_bf16 v[18:33], v[168:171], v[140:143], v[18:33]
	s_waitcnt vmcnt(0)
	v_mfma_f32_32x32x16_bf16 v[2:17], v[172:175], v[140:143], v[2:17]
	s_movk_i32 s11, 0x1000
	v_lshl_or_b32 v70, v87, 2, v86
	v_lshlrev_b64 v[86:87], 16, v[70:71]
	v_lshl_add_u64 v[86:87], s[68:69], 0, v[86:87]
	v_lshl_or_b32 v70, v67, 8, v85
	v_lshl_add_u64 v[192:193], v[86:87], 0, v[70:71]
	s_mov_b64 vcc, 0x1000
	v_lshl_add_u64 v[194:195], v[192:193], 0, vcc
	s_nop 7
	s_nop 7
	v_cvt_pk_bf16_f32 v196, v50, v51
	v_cvt_pk_bf16_f32 v197, v52, v53
	global_store_dwordx2 v[192:193], v[196:197], off
	v_cvt_pk_bf16_f32 v198, v54, v55
	v_cvt_pk_bf16_f32 v199, v56, v57
	global_store_dwordx2 v[192:193], v[198:199], off offset:512
	v_cvt_pk_bf16_f32 v200, v58, v59
	v_cvt_pk_bf16_f32 v201, v60, v61
	global_store_dwordx2 v[192:193], v[200:201], off offset:1024
	v_cvt_pk_bf16_f32 v202, v62, v63
	v_cvt_pk_bf16_f32 v203, v64, v65
	global_store_dwordx2 v[192:193], v[202:203], off offset:1536
	v_cvt_pk_bf16_f32 v196, v34, v35
	v_cvt_pk_bf16_f32 v197, v36, v37
	global_store_dwordx2 v[192:193], v[196:197], off offset:2048
	v_cvt_pk_bf16_f32 v198, v38, v39
	v_cvt_pk_bf16_f32 v199, v40, v41
	global_store_dwordx2 v[192:193], v[198:199], off offset:2560
	v_cvt_pk_bf16_f32 v200, v42, v43
	v_cvt_pk_bf16_f32 v201, v44, v45
	global_store_dwordx2 v[192:193], v[200:201], off offset:3072
	v_cvt_pk_bf16_f32 v202, v46, v47
	v_cvt_pk_bf16_f32 v203, v48, v49
	global_store_dwordx2 v[192:193], v[202:203], off offset:3584
	v_cvt_pk_bf16_f32 v196, v18, v19
	v_cvt_pk_bf16_f32 v197, v20, v21
	global_store_dwordx2 v[194:195], v[196:197], off
	v_cvt_pk_bf16_f32 v198, v22, v23
	v_cvt_pk_bf16_f32 v199, v24, v25
	global_store_dwordx2 v[194:195], v[198:199], off offset:512
	v_cvt_pk_bf16_f32 v200, v26, v27
	v_cvt_pk_bf16_f32 v201, v28, v29
	global_store_dwordx2 v[194:195], v[200:201], off offset:1024
	v_cvt_pk_bf16_f32 v202, v30, v31
	v_cvt_pk_bf16_f32 v203, v32, v33
	global_store_dwordx2 v[194:195], v[202:203], off offset:1536
	v_cvt_pk_bf16_f32 v196, v2, v3
	v_cvt_pk_bf16_f32 v197, v4, v5
	global_store_dwordx2 v[194:195], v[196:197], off offset:2048
	v_cvt_pk_bf16_f32 v198, v6, v7
	v_cvt_pk_bf16_f32 v199, v8, v9
	global_store_dwordx2 v[194:195], v[198:199], off offset:2560
	v_cvt_pk_bf16_f32 v200, v10, v11
	v_cvt_pk_bf16_f32 v201, v12, v13
	global_store_dwordx2 v[194:195], v[200:201], off offset:3072
	v_cvt_pk_bf16_f32 v202, v14, v15
	v_cvt_pk_bf16_f32 v203, v16, v17
	global_store_dwordx2 v[194:195], v[202:203], off offset:3584
	s_nop 0
	s_nop 0
.LBB0_782:
	s_andn2_saveexec_b64 s[6:7], s[6:7]
	s_cbranch_execz .LBB0_779
	v_and_b32_e32 v4, 15, v66
	v_lshlrev_b32_e32 v2, 10, v66
	v_and_b32_e32 v54, 0xffffff80, v84
	v_and_or_b32 v70, v2, s10, v69
	v_lshlrev_b32_e32 v2, 16, v4
	v_mov_b32_e32 v3, v71
	v_lshl_add_u64 v[34:35], s[2:3], 0, v[2:3]
	v_ashrrev_i32_e32 v2, 4, v54
	v_ashrrev_i32_e32 v3, 31, v2
	v_lshlrev_b64 v[30:31], 1, v[2:3]
	v_lshl_add_u64 v[2:3], v[30:31], 0, v[70:71]
	v_or_b32_e32 v36, v54, v76
	v_lshlrev_b64 v[2:3], 9, v[2:3]
	v_lshlrev_b32_e32 v46, 12, v4
	v_lshl_add_u64 v[2:3], v[78:79], 0, v[2:3]
	v_ashrrev_i32_e32 v37, 31, v36
	v_mov_b32_e32 v47, v71
	global_load_dwordx4 v[18:21], v[2:3], off
	v_lshl_add_u64 v[2:3], v[36:37], 2, v[34:35]
	v_or_b32_e32 v30, v30, v68
	v_or_b32_e32 v48, 0x800, v46
	v_mov_b32_e32 v49, v71
	global_load_dwordx4 v[22:25], v[2:3], off offset:16
	global_load_dwordx4 v[26:29], v[2:3], off
	v_lshl_add_u64 v[2:3], v[30:31], 0, v[46:47]
	v_lshl_add_u64 v[30:31], v[30:31], 0, v[48:49]
	v_lshlrev_b64 v[2:3], 9, v[2:3]
	v_lshlrev_b64 v[30:31], 9, v[30:31]
	v_lshl_add_u64 v[2:3], v[80:81], 0, v[2:3]
	v_lshl_add_u64 v[30:31], v[80:81], 0, v[30:31]
	global_load_dwordx4 v[2:5], v[2:3], off
	v_or_b32_e32 v37, 16, v54
	global_load_dwordx4 v[30:33], v[30:31], off
	v_ashrrev_i32_e32 v67, 31, v66
	s_waitcnt vmcnt(1)
	v_lshlrev_b32_e32 v6, 16, v2
	v_and_b32_e32 v7, 0xffff0000, v2
	s_waitcnt vmcnt(0)
	v_lshlrev_b32_e32 v38, 16, v30
	v_and_b32_e32 v39, 0xffff0000, v30
	v_pk_mul_f32 v[6:7], v[26:27], v[6:7]
	v_pk_mul_f32 v[26:27], v[26:27], v[38:39]
	v_ashrrev_i32_e32 v38, 4, v37
	v_ashrrev_i32_e32 v39, 31, v38
	v_lshlrev_b64 v[52:53], 1, v[38:39]
	v_lshl_add_u64 v[38:39], v[52:53], 0, v[70:71]
	v_or_b32_e32 v52, v52, v68
	v_lshl_add_u64 v[56:57], v[52:53], 0, v[46:47]
	v_lshlrev_b64 v[38:39], 9, v[38:39]
	v_ashrrev_i32_e32 v37, 31, v54
	v_lshlrev_b64 v[56:57], 9, v[56:57]
	v_lshl_add_u64 v[38:39], v[78:79], 0, v[38:39]
	v_lshl_add_u64 v[50:51], v[36:37], 2, v[34:35]
	v_lshl_add_u64 v[56:57], v[80:81], 0, v[56:57]
	global_load_dwordx4 v[38:41], v[38:39], off
	s_nop 0
	global_load_dwordx4 v[34:37], v[50:51], off offset:80
	global_load_dwordx4 v[42:45], v[50:51], off offset:64
	v_cvt_pk_bf16_f32 v2, v6, v7
	global_load_dwordx4 v[56:59], v[56:57], off
	v_lshlrev_b32_e32 v6, 16, v3
	v_and_b32_e32 v7, 0xffff0000, v3
	v_pk_mul_f32 v[6:7], v[28:29], v[6:7]
	v_lshl_add_u64 v[52:53], v[52:53], 0, v[48:49]
	v_cvt_pk_bf16_f32 v3, v6, v7
	v_lshlrev_b32_e32 v6, 16, v4
	v_and_b32_e32 v7, 0xffff0000, v4
	v_pk_mul_f32 v[6:7], v[22:23], v[6:7]
	v_lshlrev_b64 v[52:53], 9, v[52:53]
	v_cvt_pk_bf16_f32 v4, v6, v7
	v_lshlrev_b32_e32 v6, 16, v5
	v_and_b32_e32 v7, 0xffff0000, v5
	v_pk_mul_f32 v[6:7], v[24:25], v[6:7]
	v_lshl_add_u64 v[52:53], v[80:81], 0, v[52:53]
	v_cvt_pk_bf16_f32 v5, v6, v7
	v_lshlrev_b32_e32 v30, 16, v31
	v_and_b32_e32 v31, 0xffff0000, v31
	v_mfma_f32_32x32x16_bf16 v[2:17], v[18:21], v[2:5], 0
	v_mul_f32_e64 v28, v28, v30
	v_mul_f32_e64 v29, v29, v31
	v_cvt_pk_bf16_f32 v26, v26, v27
	v_cvt_pk_bf16_f32 v27, v28, v29
	v_lshlrev_b32_e32 v28, 16, v32
	v_and_b32_e32 v29, 0xffff0000, v32
	v_pk_mul_f32 v[22:23], v[22:23], v[28:29]
	s_waitcnt vmcnt(0)
	v_lshlrev_b32_e32 v60, 16, v56
	v_and_b32_e32 v61, 0xffff0000, v56
	v_pk_mul_f32 v[60:61], v[42:43], v[60:61]
	v_cvt_pk_bf16_f32 v28, v22, v23
	v_cvt_pk_bf16_f32 v56, v60, v61
	v_lshlrev_b32_e32 v60, 16, v57
	v_and_b32_e32 v61, 0xffff0000, v57
	v_pk_mul_f32 v[60:61], v[44:45], v[60:61]
	v_lshlrev_b32_e32 v22, 16, v33
	v_cvt_pk_bf16_f32 v57, v60, v61
	v_lshlrev_b32_e32 v60, 16, v58
	v_and_b32_e32 v61, 0xffff0000, v58
	v_pk_mul_f32 v[60:61], v[34:35], v[60:61]
	v_and_b32_e32 v23, 0xffff0000, v33
	v_cvt_pk_bf16_f32 v58, v60, v61
	v_lshlrev_b32_e32 v60, 16, v59
	v_and_b32_e32 v61, 0xffff0000, v59
	v_pk_mul_f32 v[60:61], v[36:37], v[60:61]
	v_pk_mul_f32 v[22:23], v[24:25], v[22:23]
	v_cvt_pk_bf16_f32 v59, v60, v61
	v_cvt_pk_bf16_f32 v29, v22, v23
	s_nop 0
	v_mfma_f32_32x32x16_bf16 v[2:17], v[38:41], v[56:59], v[2:17]
	global_load_dwordx4 v[56:59], v[52:53], off
	s_waitcnt vmcnt(0)
	v_lshlrev_b32_e32 v52, 16, v56
	v_and_b32_e32 v53, 0xffff0000, v56
	v_mul_f32_e64 v42, v42, v52
	v_mul_f32_e64 v43, v43, v53
	v_lshlrev_b32_e32 v52, 16, v57
	v_and_b32_e32 v53, 0xffff0000, v57
	v_pk_mul_f32 v[44:45], v[44:45], v[52:53]
	v_cvt_pk_bf16_f32 v42, v42, v43
	v_cvt_pk_bf16_f32 v43, v44, v45
	v_lshlrev_b32_e32 v44, 16, v58
	v_and_b32_e32 v45, 0xffff0000, v58
	v_pk_mul_f32 v[34:35], v[34:35], v[44:45]
	v_mfma_f32_32x32x16_bf16 v[18:33], v[18:21], v[26:29], 0
	v_cvt_pk_bf16_f32 v44, v34, v35
	v_lshlrev_b32_e32 v34, 16, v59
	v_and_b32_e32 v35, 0xffff0000, v59
	v_mul_f32_e64 v34, v36, v34
	v_mul_f32_e64 v35, v37, v35
	v_cvt_pk_bf16_f32 v45, v34, v35
	v_or_b32_e32 v34, 32, v54
	v_ashrrev_i32_e32 v34, 4, v34
	v_ashrrev_i32_e32 v35, 31, v34
	v_lshlrev_b64 v[52:53], 1, v[34:35]
	v_lshl_add_u64 v[34:35], v[52:53], 0, v[70:71]
	v_or_b32_e32 v52, v52, v68
	v_lshl_add_u64 v[56:57], v[52:53], 0, v[46:47]
	v_lshlrev_b64 v[34:35], 9, v[34:35]
	v_lshlrev_b64 v[56:57], 9, v[56:57]
	v_lshl_add_u64 v[34:35], v[78:79], 0, v[34:35]
	v_lshl_add_u64 v[56:57], v[80:81], 0, v[56:57]
	v_mfma_f32_32x32x16_bf16 v[18:33], v[38:41], v[42:45], v[18:33]
	global_load_dwordx4 v[34:37], v[34:35], off
	s_nop 0
	global_load_dwordx4 v[38:41], v[50:51], off offset:144
	global_load_dwordx4 v[42:45], v[50:51], off offset:128
	v_lshl_add_u64 v[52:53], v[52:53], 0, v[48:49]
	global_load_dwordx4 v[56:59], v[56:57], off
	v_lshlrev_b64 v[52:53], 9, v[52:53]
	v_lshl_add_u64 v[52:53], v[80:81], 0, v[52:53]
	s_waitcnt vmcnt(0)
	v_lshlrev_b32_e32 v60, 16, v56
	v_and_b32_e32 v61, 0xffff0000, v56
	v_pk_mul_f32 v[60:61], v[42:43], v[60:61]
	s_nop 0
	v_cvt_pk_bf16_f32 v56, v60, v61
	v_lshlrev_b32_e32 v60, 16, v57
	v_and_b32_e32 v61, 0xffff0000, v57
	v_pk_mul_f32 v[60:61], v[44:45], v[60:61]
	s_nop 0
	v_cvt_pk_bf16_f32 v57, v60, v61
	v_lshlrev_b32_e32 v60, 16, v58
	v_and_b32_e32 v61, 0xffff0000, v58
	v_pk_mul_f32 v[60:61], v[38:39], v[60:61]
	s_nop 0
	v_cvt_pk_bf16_f32 v58, v60, v61
	v_lshlrev_b32_e32 v60, 16, v59
	v_and_b32_e32 v61, 0xffff0000, v59
	v_pk_mul_f32 v[60:61], v[40:41], v[60:61]
	s_nop 0
	v_cvt_pk_bf16_f32 v59, v60, v61
	s_nop 1
	v_mfma_f32_32x32x16_bf16 v[2:17], v[34:37], v[56:59], v[2:17]
	global_load_dwordx4 v[56:59], v[52:53], off
	s_waitcnt vmcnt(0)
	v_lshlrev_b32_e32 v52, 16, v56
	v_and_b32_e32 v53, 0xffff0000, v56
	v_mul_f32_e64 v42, v42, v52
	v_mul_f32_e64 v43, v43, v53
	v_lshlrev_b32_e32 v52, 16, v57
	v_and_b32_e32 v53, 0xffff0000, v57
	v_pk_mul_f32 v[44:45], v[44:45], v[52:53]
	v_cvt_pk_bf16_f32 v42, v42, v43
	v_cvt_pk_bf16_f32 v43, v44, v45
	v_lshlrev_b32_e32 v44, 16, v58
	v_and_b32_e32 v45, 0xffff0000, v58
	v_pk_mul_f32 v[38:39], v[38:39], v[44:45]
	s_nop 0
	v_cvt_pk_bf16_f32 v44, v38, v39
	v_lshlrev_b32_e32 v38, 16, v59
	v_and_b32_e32 v39, 0xffff0000, v59
	v_pk_mul_f32 v[38:39], v[40:41], v[38:39]
	s_nop 0
	v_cvt_pk_bf16_f32 v45, v38, v39
	s_nop 1
	v_mfma_f32_32x32x16_bf16 v[18:33], v[34:37], v[42:45], v[18:33]
	v_or_b32_e32 v34, 48, v54
	v_ashrrev_i32_e32 v34, 4, v34
	v_ashrrev_i32_e32 v35, 31, v34
	v_lshlrev_b64 v[52:53], 1, v[34:35]
	v_lshl_add_u64 v[34:35], v[52:53], 0, v[70:71]
	v_or_b32_e32 v52, v52, v68
	v_lshl_add_u64 v[56:57], v[52:53], 0, v[46:47]
	v_lshlrev_b64 v[34:35], 9, v[34:35]
	v_lshlrev_b64 v[56:57], 9, v[56:57]
	v_lshl_add_u64 v[34:35], v[78:79], 0, v[34:35]
	v_lshl_add_u64 v[56:57], v[80:81], 0, v[56:57]
	global_load_dwordx4 v[34:37], v[34:35], off
	s_nop 0
	global_load_dwordx4 v[38:41], v[50:51], off offset:208
	global_load_dwordx4 v[42:45], v[50:51], off offset:192
	v_lshl_add_u64 v[52:53], v[52:53], 0, v[48:49]
	global_load_dwordx4 v[56:59], v[56:57], off
	v_lshlrev_b64 v[52:53], 9, v[52:53]
	v_lshl_add_u64 v[52:53], v[80:81], 0, v[52:53]
	s_waitcnt vmcnt(0)
	v_lshlrev_b32_e32 v60, 16, v56
	v_and_b32_e32 v61, 0xffff0000, v56
	v_pk_mul_f32 v[60:61], v[42:43], v[60:61]
	s_nop 0
	v_cvt_pk_bf16_f32 v56, v60, v61
	v_lshlrev_b32_e32 v60, 16, v57
	v_and_b32_e32 v61, 0xffff0000, v57
	v_pk_mul_f32 v[60:61], v[44:45], v[60:61]
	s_nop 0
	v_cvt_pk_bf16_f32 v57, v60, v61
	v_lshlrev_b32_e32 v60, 16, v58
	v_and_b32_e32 v61, 0xffff0000, v58
	v_pk_mul_f32 v[60:61], v[38:39], v[60:61]
	s_nop 0
	v_cvt_pk_bf16_f32 v58, v60, v61
	v_lshlrev_b32_e32 v60, 16, v59
	v_and_b32_e32 v61, 0xffff0000, v59
	v_pk_mul_f32 v[60:61], v[40:41], v[60:61]
	s_nop 0
	v_cvt_pk_bf16_f32 v59, v60, v61
	s_nop 1
	v_mfma_f32_32x32x16_bf16 v[2:17], v[34:37], v[56:59], v[2:17]
	global_load_dwordx4 v[56:59], v[52:53], off
	s_waitcnt vmcnt(0)
	v_lshlrev_b32_e32 v52, 16, v56
	v_and_b32_e32 v53, 0xffff0000, v56
	v_mul_f32_e64 v42, v42, v52
	v_mul_f32_e64 v43, v43, v53
	v_lshlrev_b32_e32 v52, 16, v57
	v_and_b32_e32 v53, 0xffff0000, v57
	v_pk_mul_f32 v[44:45], v[44:45], v[52:53]
	v_cvt_pk_bf16_f32 v42, v42, v43
	v_cvt_pk_bf16_f32 v43, v44, v45
	v_lshlrev_b32_e32 v44, 16, v58
	v_and_b32_e32 v45, 0xffff0000, v58
	v_pk_mul_f32 v[38:39], v[38:39], v[44:45]
	s_nop 0
	v_cvt_pk_bf16_f32 v44, v38, v39
	v_lshlrev_b32_e32 v38, 16, v59
	v_and_b32_e32 v39, 0xffff0000, v59
	v_pk_mul_f32 v[38:39], v[40:41], v[38:39]
	s_nop 0
	v_cvt_pk_bf16_f32 v45, v38, v39
	s_nop 1
	v_mfma_f32_32x32x16_bf16 v[18:33], v[34:37], v[42:45], v[18:33]
	v_or_b32_e32 v34, 64, v54
	v_ashrrev_i32_e32 v34, 4, v34
	v_ashrrev_i32_e32 v35, 31, v34
	v_lshlrev_b64 v[52:53], 1, v[34:35]
	v_lshl_add_u64 v[34:35], v[52:53], 0, v[70:71]
	v_or_b32_e32 v52, v52, v68
	v_lshl_add_u64 v[56:57], v[52:53], 0, v[46:47]
	v_lshlrev_b64 v[34:35], 9, v[34:35]
	v_lshlrev_b64 v[56:57], 9, v[56:57]
	v_lshl_add_u64 v[34:35], v[78:79], 0, v[34:35]
	v_lshl_add_u64 v[56:57], v[80:81], 0, v[56:57]
	global_load_dwordx4 v[34:37], v[34:35], off
	s_nop 0
	global_load_dwordx4 v[38:41], v[50:51], off offset:272
	global_load_dwordx4 v[42:45], v[50:51], off offset:256
	v_lshl_add_u64 v[52:53], v[52:53], 0, v[48:49]
	global_load_dwordx4 v[56:59], v[56:57], off
	v_lshlrev_b64 v[52:53], 9, v[52:53]
	v_lshl_add_u64 v[52:53], v[80:81], 0, v[52:53]
	s_waitcnt vmcnt(0)
	v_lshlrev_b32_e32 v60, 16, v56
	v_and_b32_e32 v61, 0xffff0000, v56
	v_pk_mul_f32 v[60:61], v[42:43], v[60:61]
	s_nop 0
	v_cvt_pk_bf16_f32 v56, v60, v61
	v_lshlrev_b32_e32 v60, 16, v57
	v_and_b32_e32 v61, 0xffff0000, v57
	v_pk_mul_f32 v[60:61], v[44:45], v[60:61]
	s_nop 0
	v_cvt_pk_bf16_f32 v57, v60, v61
	v_lshlrev_b32_e32 v60, 16, v58
	v_and_b32_e32 v61, 0xffff0000, v58
	v_pk_mul_f32 v[60:61], v[38:39], v[60:61]
	s_nop 0
	v_cvt_pk_bf16_f32 v58, v60, v61
	v_lshlrev_b32_e32 v60, 16, v59
	v_and_b32_e32 v61, 0xffff0000, v59
	v_pk_mul_f32 v[60:61], v[40:41], v[60:61]
	s_nop 0
	v_cvt_pk_bf16_f32 v59, v60, v61
	s_nop 1
	v_mfma_f32_32x32x16_bf16 v[2:17], v[34:37], v[56:59], v[2:17]
	global_load_dwordx4 v[56:59], v[52:53], off
	s_waitcnt vmcnt(0)
	v_lshlrev_b32_e32 v52, 16, v56
	v_and_b32_e32 v53, 0xffff0000, v56
	v_mul_f32_e64 v42, v42, v52
	v_mul_f32_e64 v43, v43, v53
	v_lshlrev_b32_e32 v52, 16, v57
	v_and_b32_e32 v53, 0xffff0000, v57
	v_pk_mul_f32 v[44:45], v[44:45], v[52:53]
	v_cvt_pk_bf16_f32 v42, v42, v43
	v_cvt_pk_bf16_f32 v43, v44, v45
	v_lshlrev_b32_e32 v44, 16, v58
	v_and_b32_e32 v45, 0xffff0000, v58
	v_pk_mul_f32 v[38:39], v[38:39], v[44:45]
	s_nop 0
	v_cvt_pk_bf16_f32 v44, v38, v39
	v_lshlrev_b32_e32 v38, 16, v59
	v_and_b32_e32 v39, 0xffff0000, v59
	v_pk_mul_f32 v[38:39], v[40:41], v[38:39]
	s_nop 0
	v_cvt_pk_bf16_f32 v45, v38, v39
	s_nop 1
	v_mfma_f32_32x32x16_bf16 v[18:33], v[34:37], v[42:45], v[18:33]
	v_or_b32_e32 v34, 0x50, v54
	v_ashrrev_i32_e32 v34, 4, v34
	v_ashrrev_i32_e32 v35, 31, v34
	v_lshlrev_b64 v[52:53], 1, v[34:35]
	v_lshl_add_u64 v[34:35], v[52:53], 0, v[70:71]
	v_or_b32_e32 v52, v52, v68
	v_lshl_add_u64 v[56:57], v[52:53], 0, v[46:47]
	v_lshlrev_b64 v[34:35], 9, v[34:35]
	v_lshlrev_b64 v[56:57], 9, v[56:57]
	v_lshl_add_u64 v[34:35], v[78:79], 0, v[34:35]
	v_lshl_add_u64 v[56:57], v[80:81], 0, v[56:57]
	global_load_dwordx4 v[34:37], v[34:35], off
	s_nop 0
	global_load_dwordx4 v[38:41], v[50:51], off offset:336
	global_load_dwordx4 v[42:45], v[50:51], off offset:320
	v_lshl_add_u64 v[52:53], v[52:53], 0, v[48:49]
	global_load_dwordx4 v[56:59], v[56:57], off
	v_lshlrev_b64 v[52:53], 9, v[52:53]
	v_lshl_add_u64 v[52:53], v[80:81], 0, v[52:53]
	s_waitcnt vmcnt(0)
	v_lshlrev_b32_e32 v60, 16, v56
	v_and_b32_e32 v61, 0xffff0000, v56
	v_pk_mul_f32 v[60:61], v[42:43], v[60:61]
	s_nop 0
	v_cvt_pk_bf16_f32 v56, v60, v61
	v_lshlrev_b32_e32 v60, 16, v57
	v_and_b32_e32 v61, 0xffff0000, v57
	v_pk_mul_f32 v[60:61], v[44:45], v[60:61]
	s_nop 0
	v_cvt_pk_bf16_f32 v57, v60, v61
	v_lshlrev_b32_e32 v60, 16, v58
	v_and_b32_e32 v61, 0xffff0000, v58
	v_pk_mul_f32 v[60:61], v[38:39], v[60:61]
	s_nop 0
	v_cvt_pk_bf16_f32 v58, v60, v61
	v_lshlrev_b32_e32 v60, 16, v59
	v_and_b32_e32 v61, 0xffff0000, v59
	v_pk_mul_f32 v[60:61], v[40:41], v[60:61]
	s_nop 0
	v_cvt_pk_bf16_f32 v59, v60, v61
	s_nop 1
	v_mfma_f32_32x32x16_bf16 v[2:17], v[34:37], v[56:59], v[2:17]
	global_load_dwordx4 v[56:59], v[52:53], off
	s_waitcnt vmcnt(0)
	v_lshlrev_b32_e32 v52, 16, v56
	v_and_b32_e32 v53, 0xffff0000, v56
	v_mul_f32_e64 v42, v42, v52
	v_mul_f32_e64 v43, v43, v53
	v_lshlrev_b32_e32 v52, 16, v57
	v_and_b32_e32 v53, 0xffff0000, v57
	v_pk_mul_f32 v[44:45], v[44:45], v[52:53]
	v_cvt_pk_bf16_f32 v42, v42, v43
	v_cvt_pk_bf16_f32 v43, v44, v45
	v_lshlrev_b32_e32 v44, 16, v58
	v_and_b32_e32 v45, 0xffff0000, v58
	v_pk_mul_f32 v[38:39], v[38:39], v[44:45]
	s_nop 0
	v_cvt_pk_bf16_f32 v44, v38, v39
	v_lshlrev_b32_e32 v38, 16, v59
	v_and_b32_e32 v39, 0xffff0000, v59
	v_pk_mul_f32 v[38:39], v[40:41], v[38:39]
	s_nop 0
	v_cvt_pk_bf16_f32 v45, v38, v39
	s_nop 1
	v_mfma_f32_32x32x16_bf16 v[18:33], v[34:37], v[42:45], v[18:33]
	v_or_b32_e32 v34, 0x60, v54
	v_ashrrev_i32_e32 v34, 4, v34
	v_ashrrev_i32_e32 v35, 31, v34
	v_lshlrev_b64 v[52:53], 1, v[34:35]
	v_lshl_add_u64 v[34:35], v[52:53], 0, v[70:71]
	v_or_b32_e32 v52, v52, v68
	v_lshl_add_u64 v[56:57], v[52:53], 0, v[46:47]
	v_lshlrev_b64 v[34:35], 9, v[34:35]
	v_lshlrev_b64 v[56:57], 9, v[56:57]
	v_lshl_add_u64 v[34:35], v[78:79], 0, v[34:35]
	v_lshl_add_u64 v[56:57], v[80:81], 0, v[56:57]
	global_load_dwordx4 v[34:37], v[34:35], off
	s_nop 0
	global_load_dwordx4 v[38:41], v[50:51], off offset:400
	global_load_dwordx4 v[42:45], v[50:51], off offset:384
	v_lshl_add_u64 v[52:53], v[52:53], 0, v[48:49]
	global_load_dwordx4 v[56:59], v[56:57], off
	v_lshlrev_b64 v[52:53], 9, v[52:53]
	v_lshl_add_u64 v[52:53], v[80:81], 0, v[52:53]
	s_waitcnt vmcnt(0)
	v_lshlrev_b32_e32 v60, 16, v56
	v_and_b32_e32 v61, 0xffff0000, v56
	v_pk_mul_f32 v[60:61], v[42:43], v[60:61]
	s_nop 0
	v_cvt_pk_bf16_f32 v56, v60, v61
	v_lshlrev_b32_e32 v60, 16, v57
	v_and_b32_e32 v61, 0xffff0000, v57
	v_pk_mul_f32 v[60:61], v[44:45], v[60:61]
	s_nop 0
	v_cvt_pk_bf16_f32 v57, v60, v61
	v_lshlrev_b32_e32 v60, 16, v58
	v_and_b32_e32 v61, 0xffff0000, v58
	v_pk_mul_f32 v[60:61], v[38:39], v[60:61]
	s_nop 0
	v_cvt_pk_bf16_f32 v58, v60, v61
	v_lshlrev_b32_e32 v60, 16, v59
	v_and_b32_e32 v61, 0xffff0000, v59
	v_pk_mul_f32 v[60:61], v[40:41], v[60:61]
	s_nop 0
	v_cvt_pk_bf16_f32 v59, v60, v61
	s_nop 1
	v_mfma_f32_32x32x16_bf16 v[2:17], v[34:37], v[56:59], v[2:17]
	global_load_dwordx4 v[56:59], v[52:53], off
	s_waitcnt vmcnt(0)
	v_lshlrev_b32_e32 v52, 16, v56
	v_and_b32_e32 v53, 0xffff0000, v56
	v_mul_f32_e64 v42, v42, v52
	v_mul_f32_e64 v43, v43, v53
	v_lshlrev_b32_e32 v52, 16, v57
	v_and_b32_e32 v53, 0xffff0000, v57
	v_pk_mul_f32 v[44:45], v[44:45], v[52:53]
	v_cvt_pk_bf16_f32 v42, v42, v43
	v_cvt_pk_bf16_f32 v43, v44, v45
	v_lshlrev_b32_e32 v44, 16, v58
	v_and_b32_e32 v45, 0xffff0000, v58
	v_pk_mul_f32 v[38:39], v[38:39], v[44:45]
	s_nop 0
	v_cvt_pk_bf16_f32 v44, v38, v39
	v_lshlrev_b32_e32 v38, 16, v59
	v_and_b32_e32 v39, 0xffff0000, v59
	v_pk_mul_f32 v[38:39], v[40:41], v[38:39]
	s_nop 0
	v_cvt_pk_bf16_f32 v45, v38, v39
	s_nop 1
	v_mfma_f32_32x32x16_bf16 v[18:33], v[34:37], v[42:45], v[18:33]
	v_or_b32_e32 v34, 0x70, v54
	v_ashrrev_i32_e32 v34, 4, v34
	v_ashrrev_i32_e32 v35, 31, v34
	v_lshlrev_b64 v[54:55], 1, v[34:35]
	v_lshl_add_u64 v[34:35], v[54:55], 0, v[70:71]
	v_or_b32_e32 v54, v54, v68
	v_lshl_add_u64 v[46:47], v[54:55], 0, v[46:47]
	v_lshlrev_b64 v[34:35], 9, v[34:35]
	v_lshlrev_b64 v[46:47], 9, v[46:47]
	v_lshl_add_u64 v[34:35], v[78:79], 0, v[34:35]
	v_lshl_add_u64 v[46:47], v[80:81], 0, v[46:47]
	global_load_dwordx4 v[34:37], v[34:35], off
	s_nop 0
	global_load_dwordx4 v[38:41], v[50:51], off offset:464
	global_load_dwordx4 v[42:45], v[50:51], off offset:448
	s_nop 0
	global_load_dwordx4 v[50:53], v[46:47], off
	s_waitcnt vmcnt(0)
	v_lshlrev_b32_e32 v46, 16, v50
	v_and_b32_e32 v47, 0xffff0000, v50
	v_pk_mul_f32 v[46:47], v[42:43], v[46:47]
	s_nop 0
	v_cvt_pk_bf16_f32 v50, v46, v47
	v_lshlrev_b32_e32 v46, 16, v51
	v_and_b32_e32 v47, 0xffff0000, v51
	v_pk_mul_f32 v[46:47], v[44:45], v[46:47]
	s_nop 0
	v_cvt_pk_bf16_f32 v51, v46, v47
	v_lshlrev_b32_e32 v46, 16, v52
	v_and_b32_e32 v47, 0xffff0000, v52
	v_pk_mul_f32 v[46:47], v[38:39], v[46:47]
	s_nop 0
	v_cvt_pk_bf16_f32 v52, v46, v47
	v_lshlrev_b32_e32 v46, 16, v53
	v_and_b32_e32 v47, 0xffff0000, v53
	v_pk_mul_f32 v[46:47], v[40:41], v[46:47]
	s_nop 0
	v_cvt_pk_bf16_f32 v53, v46, v47
	v_lshl_add_u64 v[46:47], v[54:55], 0, v[48:49]
	v_lshlrev_b64 v[46:47], 9, v[46:47]
	v_lshl_add_u64 v[46:47], v[80:81], 0, v[46:47]
	global_load_dwordx4 v[46:49], v[46:47], off
	v_mfma_f32_32x32x16_bf16 v[2:17], v[34:37], v[50:53], v[2:17]
	s_waitcnt vmcnt(0)
	v_lshlrev_b32_e32 v50, 16, v46
	v_and_b32_e32 v51, 0xffff0000, v46
	v_lshlrev_b32_e32 v46, 16, v47
	v_and_b32_e32 v47, 0xffff0000, v47
	v_pk_mul_f32 v[42:43], v[42:43], v[50:51]
	v_pk_mul_f32 v[44:45], v[44:45], v[46:47]
	v_cvt_pk_bf16_f32 v42, v42, v43
	v_cvt_pk_bf16_f32 v43, v44, v45
	v_lshlrev_b32_e32 v44, 16, v48
	v_and_b32_e32 v45, 0xffff0000, v48
	v_pk_mul_f32 v[38:39], v[38:39], v[44:45]
	v_cvt_pk_bf16_f32 v2, v2, v3
	v_cvt_pk_bf16_f32 v44, v38, v39
	v_lshlrev_b32_e32 v38, 16, v49
	v_and_b32_e32 v39, 0xffff0000, v49
	v_pk_mul_f32 v[38:39], v[40:41], v[38:39]
	v_cvt_pk_bf16_f32 v3, v4, v5
	v_cvt_pk_bf16_f32 v45, v38, v39
	s_nop 1
	v_mfma_f32_32x32x16_bf16 v[18:33], v[34:37], v[42:45], v[18:33]
	v_lshlrev_b64 v[34:35], 14, v[66:67]
	v_lshl_add_u64 v[4:5], v[82:83], 0, v[34:35]
	global_store_dwordx2 v[4:5], v[2:3], off
	v_cvt_pk_bf16_f32 v2, v6, v7
	v_cvt_pk_bf16_f32 v3, v8, v9
	global_store_dwordx2 v[4:5], v[2:3], off offset:512
	v_cvt_pk_bf16_f32 v2, v10, v11
	v_cvt_pk_bf16_f32 v3, v12, v13
	global_store_dwordx2 v[4:5], v[2:3], off offset:1024
	v_cvt_pk_bf16_f32 v2, v14, v15
	v_cvt_pk_bf16_f32 v3, v16, v17
	global_store_dwordx2 v[4:5], v[2:3], off offset:1536
	v_add_co_u32_e32 v4, vcc, s10, v4
	v_cvt_pk_bf16_f32 v2, v18, v19
	v_cvt_pk_bf16_f32 v3, v20, v21
	v_addc_co_u32_e32 v5, vcc, 0, v5, vcc
	global_store_dwordx2 v[4:5], v[2:3], off
	v_cvt_pk_bf16_f32 v2, v22, v23
	v_cvt_pk_bf16_f32 v3, v24, v25
	global_store_dwordx2 v[4:5], v[2:3], off offset:512
	v_cvt_pk_bf16_f32 v2, v26, v27
	v_cvt_pk_bf16_f32 v3, v28, v29
	global_store_dwordx2 v[4:5], v[2:3], off offset:1024
	v_cvt_pk_bf16_f32 v2, v30, v31
	v_cvt_pk_bf16_f32 v3, v32, v33
	global_store_dwordx2 v[4:5], v[2:3], off offset:1536
	s_branch .LBB0_779

.LBB0_1015:
	s_or_b64 exec, exec, s[0:1]
	v_readlane_b32 s0, v253, 57
	s_cmpk_lt_i32 s0, 0x100
	s_cselect_b64 s[2:3], -1, 0
	s_cmpk_gt_i32 s0, 0xff
	s_waitcnt lgkmcnt(0)
	s_barrier
	v_readlane_b32 s1, v253, 58
	s_mov_b32 s98, 0
	s_branch .LBB0_1033
.Lp6_a_entry:
	s_add_u32 s31, s62, 0xb80800
	s_addc_u32 s33, s63, 0
	s_mov_b64 s[74:75], -1
	v_mov_b32_e32 v131, 0
	s_add_i32 s76, 0, 0x18000
	s_mov_b64 s[4:5], 0x80
	s_add_i32 s77, 0, 0x10000
	s_add_i32 s78, 0, 0x1c000
	s_add_i32 s79, 0, 0x14000
	s_mov_b64 s[6:7], 0x8040080
	s_mov_b64 s[8:9], 0xb80900
	s_mov_b64 s[10:11], 0x8000100
	s_mov_b64 s[12:13], 0xc00900
	s_mov_b64 s[14:15], 0x8040100
	s_mov_b64 s[16:17], 0xb80980
	s_mov_b64 s[18:19], 0x8000180
	s_mov_b64 s[20:21], 0xc00980
	s_mov_b64 s[22:23], 0x780
	s_mov_b64 s[24:25], 0x20000
	s_mov_b32 s82, 0x20000
	s_mov_b64 s[26:27], 0x40000
	s_mov_b32 s83, 0x40000
	s_mov_b64 s[28:29], 0x60000
	s_mov_b32 s84, 0x60000
	s_mov_b32 s30, 0x3fb504f3
	v_mov_b32_e32 v1, 1
	v_readlane_b32 s0, v253, 57
	v_readlane_b32 s1, v253, 58
	s_branch .LBB0_1018

.LBB0_1024:
	s_ashr_i32 s37, s36, 31
	s_lshl_b64 s[0:1], s[36:37], 12
	s_add_u32 s74, s31, s0
	v_mov_b32_e32 v3, v131
	s_addc_u32 s75, s33, s1
	v_add_u32_e32 v155, s76, v142
	v_lshlrev_b64 v[2:3], 1, v[2:3]
	v_lshl_add_u64 v[16:17], s[74:75], 0, v[2:3]
	v_readfirstlane_b32 s39, v155
	v_add_u32_e32 v156, 0x2000, v155
	v_lshl_add_u64 v[16:17], v[16:17], 0, s[4:5]
	s_mov_b32 m0, s39
	v_mov_b32_e32 v5, v131
	v_readfirstlane_b32 s39, v156
	s_barrier
	global_load_lds_dwordx4 v[16:17], off
	v_lshlrev_b64 v[4:5], 1, v[4:5]
	s_mov_b32 m0, s39
	s_ashr_i32 s39, s38, 31
	v_lshl_add_u64 v[16:17], s[74:75], 0, v[4:5]
	s_lshl_b64 s[74:75], s[38:39], 11
	s_add_u32 s74, s80, s74
	v_lshl_add_u64 v[16:17], v[16:17], 0, s[4:5]
	s_addc_u32 s75, s81, s75
	v_add_u32_e32 v157, s77, v142
	global_load_lds_dwordx4 v[16:17], off
	v_lshl_add_u64 v[16:17], v[130:131], 1, s[74:75]
	v_readfirstlane_b32 s39, v157
	v_lshl_add_u64 v[16:17], v[16:17], 0, s[4:5]
	s_mov_b32 m0, s39
	v_mov_b32_e32 v133, v131
	global_load_lds_dwordx4 v[16:17], off
	v_lshlrev_b64 v[16:17], 1, v[132:133]
	v_lshl_add_u64 v[18:19], s[74:75], 0, v[16:17]
	s_or_b32 s74, s36, 0x80
	s_ashr_i32 s75, s74, 31
	s_lshl_b64 s[74:75], s[74:75], 12
	v_add_u32_e32 v158, 0x2000, v157
	s_add_u32 s74, s31, s74
	v_readfirstlane_b32 s39, v158
	s_addc_u32 s75, s33, s75
	v_add_u32_e32 v159, s78, v142
	v_lshl_add_u64 v[18:19], v[18:19], 0, s[4:5]
	s_mov_b32 m0, s39
	v_lshl_add_u64 v[2:3], s[74:75], 0, v[2:3]
	v_readfirstlane_b32 s39, v159
	global_load_lds_dwordx4 v[18:19], off
	v_lshl_add_u64 v[2:3], v[2:3], 0, s[4:5]
	s_mov_b32 m0, s39
	v_add_u32_e32 v160, 0x2000, v159
	global_load_lds_dwordx4 v[2:3], off
	v_lshl_add_u64 v[2:3], s[74:75], 0, v[4:5]
	v_readfirstlane_b32 s39, v160
	v_lshl_add_u64 v[2:3], v[2:3], 0, s[4:5]
	s_mov_b32 m0, s39
	v_and_b32_e32 v15, 15, v10
	global_load_lds_dwordx4 v[2:3], off
	v_lshlrev_b32_e32 v3, 2, v10
	v_and_b32_e32 v20, 48, v10
	v_lshlrev_b32_e32 v2, 6, v15
	v_and_b32_e32 v3, 32, v3
	v_lshlrev_b32_e32 v10, 6, v10
	v_bitop3_b32 v2, v2, v3, v20 bitop3:0x36
	v_and_b32_e32 v10, 0x3c0, v10
	v_add_u32_e32 v161, 0, v2
	v_add_u32_e32 v4, s76, v2
	v_add_u32_e32 v5, s78, v2
	v_bitop3_b32 v3, v10, v3, v20 bitop3:0x36
	v_add_u32_e32 v10, s77, v2
	v_add_u32_e32 v15, s79, v2
	v_lshrrev_b32_e32 v9, 1, v9
	v_lshlrev_b32_e32 v2, 11, v6
	v_lshl_add_u32 v2, v9, 15, v2
	v_or_b32_e32 v2, v2, v7
	v_add_u32_e32 v162, 0, v3
	v_add_u32_e32 v163, s77, v3
	v_add_u32_e32 v164, s79, v3
	v_add_u32_e32 v2, v2, v8
	v_mov_b32_e32 v3, v131
	v_lshl_add_u64 v[134:135], v[2:3], 1, s[0:1]
	v_lshlrev_b32_e32 v2, 14, v11
	v_and_b32_e32 v2, 0xffff8000, v2
	v_lshl_add_u32 v2, v12, 11, v2
	v_or_b32_e32 v2, v2, v13
	v_add_u32_e32 v2, v2, v14
	v_lshl_add_u64 v[136:137], v[2:3], 1, s[0:1]
	s_sub_i32 s1, s87, s89
	s_lshl_b32 s87, s88, 5
	s_sub_i32 s1, s1, s87
	s_sext_i32_i8 s1, s1
	s_lshl_b32 s0, s88, 11
	s_lshl_b32 s1, s1, 8
	v_lshlrev_b32_e32 v2, 10, v6
	s_add_i32 s0, s0, s1
	v_lshl_add_u32 v2, v9, 14, v2
	s_ashr_i32 s1, s0, 31
	v_or_b32_e32 v2, v2, v7
	s_waitcnt vmcnt(6)
	s_lshl_b32 s39, s45, 6
	s_lshl_b64 s[0:1], s[0:1], 11
	v_add_u32_e32 v2, v2, v8
	s_and_b32 s39, s39, 0x3000
	s_lshl_b32 s71, s71, 13
	v_lshl_add_u64 v[138:139], v[2:3], 1, s[0:1]
	s_or_b32 s74, s71, 0x800
	s_or_b32 s75, s71, 0x1000
	s_or_b32 s86, s71, 0x1800
	v_lshl_add_u64 v[140:141], s[0:1], 0, v[16:17]
	s_mov_b32 s87, -2
	v_add_u32_e32 v154, s39, v4
	v_add_u32_e32 v153, s71, v10
	v_add_u32_e32 v152, s39, v5
	v_add_u32_e32 v151, s71, v15
	s_mov_b64 s[0:1], s[62:63]
	s_barrier
	v_mov_b32_e32 v2, v222
	v_mov_b32_e32 v3, v223
	v_mov_b32_e32 v4, v224
	v_mov_b32_e32 v5, v225
	v_mov_b32_e32 v6, v226
	v_mov_b32_e32 v7, v227
	v_mov_b32_e32 v8, v228
	v_mov_b32_e32 v9, v229
	v_mov_b32_e32 v10, v230
	v_mov_b32_e32 v11, v231
	v_mov_b32_e32 v12, v232
	v_mov_b32_e32 v13, v233
	v_mov_b32_e32 v14, v234
	v_mov_b32_e32 v15, v235
	v_mov_b32_e32 v16, v236
	v_mov_b32_e32 v17, v237
	v_mov_b32_e32 v18, v238
	v_mov_b32_e32 v19, v239
	v_mov_b32_e32 v20, v240
	v_mov_b32_e32 v21, v241
	v_mov_b32_e32 v22, v242
	v_mov_b32_e32 v23, v243
	v_mov_b32_e32 v24, v244
	v_mov_b32_e32 v25, v245

.LBB0_1032:
	v_readlane_b32 s0, v253, 57
	s_nop 3
	s_cmpk_lt_i32 s0, 0x100
	s_cselect_b64 s[2:3], -1, 0
	v_readlane_b32 s70, v254, 10
	v_readlane_b32 s74, v254, 12
	v_readlane_b32 s71, v254, 11
	v_readlane_b32 s75, v254, 13
.LBB0_1033:
	v_readlane_b32 s86, v253, 57
	s_waitcnt vmcnt(0)
	v_readlane_b32 s87, v253, 58
	v_cndmask_b32_e64 v1, 0, 1, s[2:3]
	s_mov_b32 s92, s86
	v_readlane_b32 s36, v253, 55
	v_readlane_b32 s80, v254, 40
	v_readlane_b32 s86, v254, 38
	v_cmp_ne_u32_e64 s[4:5], 1, v1
	s_andn2_b64 vcc, exec, s[2:3]
	v_readlane_b32 s37, v253, 56
	v_readlane_b32 s93, v254, 9
	v_readlane_b32 s81, v254, 41
	v_readlane_b32 s87, v254, 39
	s_cmp_eq_u32 s98, 1
	s_cbranch_scc1 .LBB0_1051
	s_cbranch_vccnz .LBB0_1051
	s_mov_b64 s[70:71], -1
	v_mov_b32_e32 v139, 0
	s_add_i32 s33, 0, 0x18000
	s_mov_b64 s[2:3], 0x80
	s_add_i32 s72, 0, 0x10000
	s_add_i32 s73, 0, 0x1c000
	s_add_i32 s74, 0, 0x14000
	s_mov_b64 s[6:7], 0x6040080
	s_mov_b64 s[8:9], 0xb80100
	s_mov_b64 s[10:11], 0x6000100
	s_mov_b64 s[12:13], 0xc00100
	s_mov_b64 s[14:15], 0x6040100
	s_mov_b64 s[16:17], 0xb80180
	s_mov_b64 s[18:19], 0x6000180
	s_mov_b64 s[20:21], 0xc00180
	s_mov_b64 s[22:23], 0x780
	s_mov_b64 s[24:25], 0x20000
	s_mov_b64 s[26:27], 0x40000
	s_mov_b64 s[28:29], 0x60000
	v_mov_b32_e32 v1, 0x3727c5ac
	s_mov_b32 s75, 0x800000
	v_mov_b32_e32 v150, 1
	s_mov_b32 s0, s92
	s_branch .LBB0_1036
.Lp6_junction:
	v_lshrrev_b32_e32 v166, 8, v0
	v_bfe_u32 v167, v0, 4, 2
	v_lshlrev_b32_e32 v166, 6, v166
	v_lshl_add_u32 v166, v167, 2, v166
	v_add_u32_e32 v166, s34, v166
	v_mov_b32_e32 v167, 0
	v_lshlrev_b64 v[166:167], 2, v[166:167]
	v_lshl_add_u64 v[166:167], s[46:47], 0, v[166:167]
	global_load_dwordx4 v[168:171], v[166:167], off offset:0
	global_load_dwordx4 v[172:175], v[166:167], off offset:64
	global_load_dwordx4 v[176:179], v[166:167], off offset:128
	global_load_dwordx4 v[180:183], v[166:167], off offset:192
	global_load_dwordx4 v[184:187], v[166:167], off offset:512
	global_load_dwordx4 v[188:191], v[166:167], off offset:576
	global_load_dwordx4 v[192:195], v[166:167], off offset:640
	global_load_dwordx4 v[196:199], v[166:167], off offset:704
	s_waitcnt vmcnt(0)
	v_fmamk_f32 v168, v168, 0x3a800000, v1
	v_fmamk_f32 v169, v169, 0x3a800000, v1
	v_fmamk_f32 v170, v170, 0x3a800000, v1
	v_fmamk_f32 v171, v171, 0x3a800000, v1
	v_fmamk_f32 v172, v172, 0x3a800000, v1
	v_fmamk_f32 v173, v173, 0x3a800000, v1
	v_fmamk_f32 v174, v174, 0x3a800000, v1
	v_fmamk_f32 v175, v175, 0x3a800000, v1
	v_fmamk_f32 v176, v176, 0x3a800000, v1
	v_fmamk_f32 v177, v177, 0x3a800000, v1
	v_fmamk_f32 v178, v178, 0x3a800000, v1
	v_fmamk_f32 v179, v179, 0x3a800000, v1
	v_fmamk_f32 v180, v180, 0x3a800000, v1
	v_fmamk_f32 v181, v181, 0x3a800000, v1
	v_fmamk_f32 v182, v182, 0x3a800000, v1
	v_fmamk_f32 v183, v183, 0x3a800000, v1
	v_fmamk_f32 v184, v184, 0x3a800000, v1
	v_fmamk_f32 v185, v185, 0x3a800000, v1
	v_fmamk_f32 v186, v186, 0x3a800000, v1
	v_fmamk_f32 v187, v187, 0x3a800000, v1
	v_fmamk_f32 v188, v188, 0x3a800000, v1
	v_fmamk_f32 v189, v189, 0x3a800000, v1
	v_fmamk_f32 v190, v190, 0x3a800000, v1
	v_fmamk_f32 v191, v191, 0x3a800000, v1
	v_fmamk_f32 v192, v192, 0x3a800000, v1
	v_fmamk_f32 v193, v193, 0x3a800000, v1
	v_fmamk_f32 v194, v194, 0x3a800000, v1
	v_fmamk_f32 v195, v195, 0x3a800000, v1
	v_fmamk_f32 v196, v196, 0x3a800000, v1
	v_fmamk_f32 v197, v197, 0x3a800000, v1
	v_fmamk_f32 v198, v198, 0x3a800000, v1
	v_fmamk_f32 v199, v199, 0x3a800000, v1
	v_rsq_f32_e32 v168, v168
	v_rsq_f32_e32 v169, v169
	v_rsq_f32_e32 v170, v170
	v_rsq_f32_e32 v171, v171
	v_rsq_f32_e32 v172, v172
	v_rsq_f32_e32 v173, v173
	v_rsq_f32_e32 v174, v174
	v_rsq_f32_e32 v175, v175
	v_rsq_f32_e32 v176, v176
	v_rsq_f32_e32 v177, v177
	v_rsq_f32_e32 v178, v178
	v_rsq_f32_e32 v179, v179
	v_rsq_f32_e32 v180, v180
	v_rsq_f32_e32 v181, v181
	v_rsq_f32_e32 v182, v182
	v_rsq_f32_e32 v183, v183
	v_rsq_f32_e32 v184, v184
	v_rsq_f32_e32 v185, v185
	v_rsq_f32_e32 v186, v186
	v_rsq_f32_e32 v187, v187
	v_rsq_f32_e32 v188, v188
	v_rsq_f32_e32 v189, v189
	v_rsq_f32_e32 v190, v190
	v_rsq_f32_e32 v191, v191
	v_rsq_f32_e32 v192, v192
	v_rsq_f32_e32 v193, v193
	v_rsq_f32_e32 v194, v194
	v_rsq_f32_e32 v195, v195
	v_rsq_f32_e32 v196, v196
	v_rsq_f32_e32 v197, v197
	v_rsq_f32_e32 v198, v198
	v_rsq_f32_e32 v199, v199
	s_nop 0
	v_mul_f32_e32 v126, v126, v168
	v_mul_f32_e32 v127, v127, v169
	v_mul_f32_e32 v128, v128, v170
	v_mul_f32_e32 v129, v129, v171
	v_mul_f32_e32 v98, v98, v168
	v_mul_f32_e32 v99, v99, v169
	v_mul_f32_e32 v100, v100, v170
	v_mul_f32_e32 v101, v101, v171
	v_mul_f32_e32 v102, v102, v172
	v_mul_f32_e32 v103, v103, v173
	v_mul_f32_e32 v104, v104, v174
	v_mul_f32_e32 v105, v105, v175
	v_mul_f32_e32 v106, v106, v172
	v_mul_f32_e32 v107, v107, v173
	v_mul_f32_e32 v108, v108, v174
	v_mul_f32_e32 v109, v109, v175
	v_mul_f32_e32 v110, v110, v176
	v_mul_f32_e32 v111, v111, v177
	v_mul_f32_e32 v112, v112, v178
	v_mul_f32_e32 v113, v113, v179
	v_mul_f32_e32 v114, v114, v176
	v_mul_f32_e32 v115, v115, v177
	v_mul_f32_e32 v116, v116, v178
	v_mul_f32_e32 v117, v117, v179
	v_mul_f32_e32 v118, v118, v180
	v_mul_f32_e32 v119, v119, v181
	v_mul_f32_e32 v120, v120, v182
	v_mul_f32_e32 v121, v121, v183
	v_mul_f32_e32 v122, v122, v180
	v_mul_f32_e32 v123, v123, v181
	v_mul_f32_e32 v124, v124, v182
	v_mul_f32_e32 v125, v125, v183
	v_mul_f32_e32 v66, v66, v168
	v_mul_f32_e32 v67, v67, v169
	v_mul_f32_e32 v68, v68, v170
	v_mul_f32_e32 v69, v69, v171
	v_mul_f32_e32 v70, v70, v168
	v_mul_f32_e32 v71, v71, v169
	v_mul_f32_e32 v72, v72, v170
	v_mul_f32_e32 v73, v73, v171
	v_mul_f32_e32 v74, v74, v172
	v_mul_f32_e32 v75, v75, v173
	v_mul_f32_e32 v76, v76, v174
	v_mul_f32_e32 v77, v77, v175
	v_mul_f32_e32 v78, v78, v172
	v_mul_f32_e32 v79, v79, v173
	v_mul_f32_e32 v80, v80, v174
	v_mul_f32_e32 v81, v81, v175
	v_mul_f32_e32 v82, v82, v176
	v_mul_f32_e32 v83, v83, v177
	v_mul_f32_e32 v84, v84, v178
	v_mul_f32_e32 v85, v85, v179
	v_mul_f32_e32 v86, v86, v176
	v_mul_f32_e32 v87, v87, v177
	v_mul_f32_e32 v88, v88, v178
	v_mul_f32_e32 v89, v89, v179
	v_mul_f32_e32 v90, v90, v180
	v_mul_f32_e32 v91, v91, v181
	v_mul_f32_e32 v92, v92, v182
	v_mul_f32_e32 v93, v93, v183
	v_mul_f32_e32 v94, v94, v180
	v_mul_f32_e32 v95, v95, v181
	v_mul_f32_e32 v96, v96, v182
	v_mul_f32_e32 v97, v97, v183
	v_mul_f32_e32 v34, v34, v184
	v_mul_f32_e32 v35, v35, v185
	v_mul_f32_e32 v36, v36, v186
	v_mul_f32_e32 v37, v37, v187
	v_mul_f32_e32 v38, v38, v184
	v_mul_f32_e32 v39, v39, v185
	v_mul_f32_e32 v40, v40, v186
	v_mul_f32_e32 v41, v41, v187
	v_mul_f32_e32 v42, v42, v188
	v_mul_f32_e32 v43, v43, v189
	v_mul_f32_e32 v44, v44, v190
	v_mul_f32_e32 v45, v45, v191
	v_mul_f32_e32 v46, v46, v188
	v_mul_f32_e32 v47, v47, v189
	v_mul_f32_e32 v48, v48, v190
	v_mul_f32_e32 v49, v49, v191
	v_mul_f32_e32 v50, v50, v192
	v_mul_f32_e32 v51, v51, v193
	v_mul_f32_e32 v52, v52, v194
	v_mul_f32_e32 v53, v53, v195
	v_mul_f32_e32 v54, v54, v192
	v_mul_f32_e32 v55, v55, v193
	v_mul_f32_e32 v56, v56, v194
	v_mul_f32_e32 v57, v57, v195
	v_mul_f32_e32 v58, v58, v196
	v_mul_f32_e32 v59, v59, v197
	v_mul_f32_e32 v60, v60, v198
	v_mul_f32_e32 v61, v61, v199
	v_mul_f32_e32 v62, v62, v196
	v_mul_f32_e32 v63, v63, v197
	v_mul_f32_e32 v64, v64, v198
	v_mul_f32_e32 v65, v65, v199
	v_mul_f32_e32 v2, v2, v184
	v_mul_f32_e32 v3, v3, v185
	v_mul_f32_e32 v4, v4, v186
	v_mul_f32_e32 v5, v5, v187
	v_mul_f32_e32 v6, v6, v184
	v_mul_f32_e32 v7, v7, v185
	v_mul_f32_e32 v8, v8, v186
	v_mul_f32_e32 v9, v9, v187
	v_mul_f32_e32 v10, v10, v188
	v_mul_f32_e32 v11, v11, v189
	v_mul_f32_e32 v12, v12, v190
	v_mul_f32_e32 v13, v13, v191
	v_mul_f32_e32 v14, v14, v188
	v_mul_f32_e32 v15, v15, v189
	v_mul_f32_e32 v16, v16, v190
	v_mul_f32_e32 v17, v17, v191
	v_mul_f32_e32 v18, v18, v192
	v_mul_f32_e32 v19, v19, v193
	v_mul_f32_e32 v20, v20, v194
	v_mul_f32_e32 v21, v21, v195
	v_mul_f32_e32 v22, v22, v192
	v_mul_f32_e32 v23, v23, v193
	v_mul_f32_e32 v24, v24, v194
	v_mul_f32_e32 v25, v25, v195
	v_mul_f32_e32 v26, v26, v196
	v_mul_f32_e32 v27, v27, v197
	v_mul_f32_e32 v28, v28, v198
	v_mul_f32_e32 v29, v29, v199
	v_mul_f32_e32 v30, v30, v196
	v_mul_f32_e32 v31, v31, v197
	v_mul_f32_e32 v32, v32, v198
	v_mul_f32_e32 v33, v33, v199
	v_mov_b32_e32 v242, v58
	v_mov_b32_e32 v243, v59
	v_mov_b32_e32 v244, v60
	v_mov_b32_e32 v245, v61
	v_mov_b32_e32 v238, v62
	v_mov_b32_e32 v239, v63
	v_mov_b32_e32 v240, v64
	v_mov_b32_e32 v241, v65
	v_mov_b32_e32 v234, v2
	v_mov_b32_e32 v235, v3
	v_mov_b32_e32 v236, v4
	v_mov_b32_e32 v237, v5
	v_mov_b32_e32 v230, v6
	v_mov_b32_e32 v231, v7
	v_mov_b32_e32 v232, v8
	v_mov_b32_e32 v233, v9
	v_mov_b32_e32 v226, v10
	v_mov_b32_e32 v227, v11
	v_mov_b32_e32 v228, v12
	v_mov_b32_e32 v229, v13
	v_mov_b32_e32 v222, v14
	v_mov_b32_e32 v223, v15
	v_mov_b32_e32 v224, v16
	v_mov_b32_e32 v225, v17
	v_mov_b32_e32 v62, v82
	v_mov_b32_e32 v63, v83
	v_mov_b32_e32 v64, v84
	v_mov_b32_e32 v65, v85
	v_mov_b32_e32 v58, v86
	v_mov_b32_e32 v59, v87
	v_mov_b32_e32 v60, v88
	v_mov_b32_e32 v61, v89
	v_mov_b32_e32 v82, v74
	v_mov_b32_e32 v83, v75
	v_mov_b32_e32 v84, v76
	v_mov_b32_e32 v85, v77
	v_mov_b32_e32 v86, v30
	v_mov_b32_e32 v87, v31
	v_mov_b32_e32 v88, v32
	v_mov_b32_e32 v89, v33
	v_mov_b32_e32 v30, v50
	v_mov_b32_e32 v31, v51
	v_mov_b32_e32 v32, v52
	v_mov_b32_e32 v33, v53
	v_mov_b32_e32 v74, v22
	v_mov_b32_e32 v75, v23
	v_mov_b32_e32 v76, v24
	v_mov_b32_e32 v77, v25
	v_mov_b32_e32 v50, v94
	v_mov_b32_e32 v51, v95
	v_mov_b32_e32 v52, v96
	v_mov_b32_e32 v53, v97
	v_mov_b32_e32 v94, v66
	v_mov_b32_e32 v95, v67
	v_mov_b32_e32 v96, v68
	v_mov_b32_e32 v97, v69
	v_mov_b32_e32 v66, v78
	v_mov_b32_e32 v67, v79
	v_mov_b32_e32 v68, v80
	v_mov_b32_e32 v69, v81
	v_mov_b32_e32 v78, v26
	v_mov_b32_e32 v79, v27
	v_mov_b32_e32 v80, v28
	v_mov_b32_e32 v81, v29
	v_mov_b32_e32 v26, v54
	v_mov_b32_e32 v27, v55
	v_mov_b32_e32 v28, v56
	v_mov_b32_e32 v29, v57
	v_mov_b32_e32 v54, v90
	v_mov_b32_e32 v55, v91
	v_mov_b32_e32 v56, v92
	v_mov_b32_e32 v57, v93
	v_mov_b32_e32 v90, v70
	v_mov_b32_e32 v91, v71
	v_mov_b32_e32 v92, v72
	v_mov_b32_e32 v93, v73
	v_mov_b32_e32 v70, v18
	v_mov_b32_e32 v71, v19
	v_mov_b32_e32 v72, v20
	v_mov_b32_e32 v73, v21
	v_mov_b32_e32 v250, v122
	v_mov_b32_e32 v122, v98
	v_mov_b32_e32 v98, v250
	v_mov_b32_e32 v250, v123
	v_mov_b32_e32 v123, v99
	v_mov_b32_e32 v99, v250
	v_mov_b32_e32 v250, v124
	v_mov_b32_e32 v124, v100
	v_mov_b32_e32 v100, v250
	v_mov_b32_e32 v250, v125
	v_mov_b32_e32 v125, v101
	v_mov_b32_e32 v101, v250
	v_mov_b32_e32 v250, v118
	v_mov_b32_e32 v118, v102
	v_mov_b32_e32 v102, v250
	v_mov_b32_e32 v250, v119
	v_mov_b32_e32 v119, v103
	v_mov_b32_e32 v103, v250
	v_mov_b32_e32 v250, v120
	v_mov_b32_e32 v120, v104
	v_mov_b32_e32 v104, v250
	v_mov_b32_e32 v250, v121
	v_mov_b32_e32 v121, v105
	v_mov_b32_e32 v105, v250
	v_mov_b32_e32 v250, v114
	v_mov_b32_e32 v114, v106
	v_mov_b32_e32 v106, v250
	v_mov_b32_e32 v250, v115
	v_mov_b32_e32 v115, v107
	v_mov_b32_e32 v107, v250
	v_mov_b32_e32 v250, v116
	v_mov_b32_e32 v116, v108
	v_mov_b32_e32 v108, v250
	v_mov_b32_e32 v250, v117
	v_mov_b32_e32 v117, v109
	v_mov_b32_e32 v109, v250
	v_mov_b32_e32 v250, v46
	v_mov_b32_e32 v46, v34
	v_mov_b32_e32 v34, v250
	v_mov_b32_e32 v250, v47
	v_mov_b32_e32 v47, v35
	v_mov_b32_e32 v35, v250
	v_mov_b32_e32 v250, v48
	v_mov_b32_e32 v48, v36
	v_mov_b32_e32 v36, v250
	v_mov_b32_e32 v250, v49
	v_mov_b32_e32 v49, v37
	v_mov_b32_e32 v37, v250
	v_mov_b32_e32 v250, v42
	v_mov_b32_e32 v42, v38
	v_mov_b32_e32 v38, v250
	v_mov_b32_e32 v250, v43
	v_mov_b32_e32 v43, v39
	v_mov_b32_e32 v39, v250
	v_mov_b32_e32 v250, v44
	v_mov_b32_e32 v44, v40
	v_mov_b32_e32 v40, v250
	v_mov_b32_e32 v250, v45
	v_mov_b32_e32 v45, v41
	v_mov_b32_e32 v41, v250
	s_add_u32 s80, s62, 0x8000000
	s_addc_u32 s81, s63, 0
	v_readlane_b32 s64, v255, 42
	v_readlane_b32 s65, v255, 43
	s_mov_b32 s98, 1
	s_branch .Lp6_a_entry

.LBB0_1531:
	v_mbcnt_lo_u32_b32 v148, -1, 0
	v_mbcnt_hi_u32_b32 v148, -1, v148
	v_xor_b32_e32 v149, 32, v148
	v_lshlrev_b32_e32 v149, 2, v149
	v_mov_b32_e32 v150, 0x3727c5ac
	v_lshlrev_b32_e32 v151, 3, v148
	global_load_dwordx4 v[64:67], v[12:13], off
	global_load_dwordx4 v[68:71], v[12:13], off offset:1024
	global_load_dwordx4 v[72:75], v[12:13], off offset:2048
	global_load_dwordx4 v[76:79], v[12:13], off offset:3072
	global_load_dwordx4 v[80:83], v[14:15], off
	global_load_dwordx4 v[84:87], v[14:15], off offset:1024
	global_load_dwordx4 v[88:91], v[14:15], off offset:2048
	global_load_dwordx4 v[92:95], v[14:15], off offset:3072
	v_ashrrev_i32_e32 v159, 31, v16
	v_mov_b32_e32 v158, v16
	v_lshlrev_b64 v[158:159], 12, v[158:159]
	v_lshl_add_u64 v[152:153], v[10:11], 0, v[158:159]
	global_load_dwordx4 v[96:99], v[152:153], off
	global_load_dwordx4 v[100:103], v[152:153], off offset:1024
	global_load_dwordx4 v[104:107], v[152:153], off offset:2048
	global_load_dwordx4 v[108:111], v[152:153], off offset:3072
	s_add_i32 s99, s10, s96
	s_cmpk_lt_i32 s99, 0x800
	s_cselect_b32 s99, s2, 0
	v_add_u32_e32 v156, s99, v16
	v_ashrrev_i32_e32 v159, 31, v156
	v_mov_b32_e32 v158, v156
	v_lshlrev_b64 v[158:159], 12, v[158:159]
	v_lshl_add_u64 v[154:155], v[10:11], 0, v[158:159]
	global_load_dwordx4 v[112:115], v[154:155], off
	global_load_dwordx4 v[116:119], v[154:155], off offset:1024
	global_load_dwordx4 v[120:123], v[154:155], off offset:2048
	global_load_dwordx4 v[124:127], v[154:155], off offset:3072
	s_waitcnt vmcnt(4)
	s_branch .Lln_p10_procA
.Lln_p10_loopA:
	s_add_i32 s99, s10, s96
	s_cmpk_lt_i32 s99, 0x800
	s_cselect_b32 s99, s2, 0
	v_add_u32_e32 v156, s99, v16
	v_ashrrev_i32_e32 v159, 31, v156
	v_mov_b32_e32 v158, v156
	v_lshlrev_b64 v[158:159], 12, v[158:159]
	v_lshl_add_u64 v[154:155], v[10:11], 0, v[158:159]
	global_load_dwordx4 v[112:115], v[154:155], off
	global_load_dwordx4 v[116:119], v[154:155], off offset:1024
	global_load_dwordx4 v[120:123], v[154:155], off offset:2048
	global_load_dwordx4 v[124:127], v[154:155], off offset:3072
	s_waitcnt vmcnt(9)
.Lln_p10_procA:
	v_add_f32_e32 v128, v96, v97
	v_add_f32_e32 v129, v100, v101
	v_add_f32_e32 v130, v104, v105
	v_add_f32_e32 v131, v108, v109
	v_add_f32_e32 v128, v98, v128
	v_add_f32_e32 v129, v102, v129
	v_add_f32_e32 v130, v106, v130
	v_add_f32_e32 v131, v110, v131
	v_add_f32_e32 v128, v99, v128
	v_add_f32_e32 v129, v103, v129
	v_add_f32_e32 v130, v107, v130
	v_add_f32_e32 v131, v111, v131
	v_add_f32_e32 v132, v128, v129
	v_add_f32_e32 v132, v132, v130
	v_add_f32_e32 v132, v132, v131
	s_nop 1
	v_add_f32_dpp v132, v132, v132 quad_perm:[1,0,3,2] row_mask:0xf bank_mask:0xf
	s_nop 1
	v_add_f32_dpp v132, v132, v132 quad_perm:[2,3,0,1] row_mask:0xf bank_mask:0xf
	s_nop 1
	v_add_f32_dpp v132, v132, v132 row_half_mirror row_mask:0xf bank_mask:0xf
	s_nop 1
	v_add_f32_dpp v132, v132, v132 row_mirror row_mask:0xf bank_mask:0xf
	ds_swizzle_b32 v147, v132 offset:0x401f
	s_waitcnt lgkmcnt(0)
	v_add_f32_e32 v132, v132, v147
	ds_bpermute_b32 v147, v149, v132
	s_waitcnt lgkmcnt(0)
	v_add_f32_e32 v132, v132, v147
	v_mul_f32_e32 v133, 0x3a800000, v132
	v_sub_f32_e32 v96, v96, v133
	v_sub_f32_e32 v97, v97, v133
	v_sub_f32_e32 v98, v98, v133
	v_sub_f32_e32 v99, v99, v133
	v_sub_f32_e32 v100, v100, v133
	v_sub_f32_e32 v101, v101, v133
	v_sub_f32_e32 v102, v102, v133
	v_sub_f32_e32 v103, v103, v133
	v_sub_f32_e32 v104, v104, v133
	v_sub_f32_e32 v105, v105, v133
	v_sub_f32_e32 v106, v106, v133
	v_sub_f32_e32 v107, v107, v133
	v_sub_f32_e32 v108, v108, v133
	v_sub_f32_e32 v109, v109, v133
	v_sub_f32_e32 v110, v110, v133
	v_sub_f32_e32 v111, v111, v133
	v_mul_f32_e32 v134, v96, v96
	v_mul_f32_e32 v135, v97, v97
	v_add_f32_e32 v134, v134, v135
	v_mul_f32_e32 v135, v98, v98
	v_add_f32_e32 v134, v135, v134
	v_mul_f32_e32 v135, v99, v99
	v_add_f32_e32 v134, v135, v134
	v_mul_f32_e32 v135, v100, v100
	v_add_f32_e32 v134, v135, v134
	v_mul_f32_e32 v135, v101, v101
	v_add_f32_e32 v134, v135, v134
	v_mul_f32_e32 v135, v102, v102
	v_add_f32_e32 v134, v135, v134
	v_mul_f32_e32 v135, v103, v103
	v_add_f32_e32 v134, v135, v134
	v_mul_f32_e32 v135, v104, v104
	v_add_f32_e32 v134, v135, v134
	v_mul_f32_e32 v135, v105, v105
	v_add_f32_e32 v134, v135, v134
	v_mul_f32_e32 v135, v106, v106
	v_add_f32_e32 v134, v135, v134
	v_mul_f32_e32 v135, v107, v107
	v_add_f32_e32 v134, v135, v134
	v_mul_f32_e32 v135, v108, v108
	v_add_f32_e32 v134, v135, v134
	v_mul_f32_e32 v135, v109, v109
	v_add_f32_e32 v134, v135, v134
	v_mul_f32_e32 v135, v110, v110
	v_add_f32_e32 v134, v135, v134
	v_mul_f32_e32 v135, v111, v111
	v_add_f32_e32 v134, v135, v134
	s_nop 1
	v_add_f32_dpp v134, v134, v134 quad_perm:[1,0,3,2] row_mask:0xf bank_mask:0xf
	s_nop 1
	v_add_f32_dpp v134, v134, v134 quad_perm:[2,3,0,1] row_mask:0xf bank_mask:0xf
	s_nop 1
	v_add_f32_dpp v134, v134, v134 row_half_mirror row_mask:0xf bank_mask:0xf
	s_nop 1
	v_add_f32_dpp v134, v134, v134 row_mirror row_mask:0xf bank_mask:0xf
	ds_swizzle_b32 v147, v134 offset:0x401f
	s_waitcnt lgkmcnt(0)
	v_add_f32_e32 v134, v134, v147
	ds_bpermute_b32 v147, v149, v134
	s_waitcnt lgkmcnt(0)
	v_add_f32_e32 v134, v134, v147
	v_fmamk_f32 v134, v134, 0x3a800000, v150
	v_rsq_f32_e32 v134, v134
	s_nop 0
	v_mul_f32_e32 v96, v96, v134
	v_mul_f32_e32 v97, v97, v134
	v_mul_f32_e32 v98, v98, v134
	v_mul_f32_e32 v99, v99, v134
	v_mul_f32_e32 v100, v100, v134
	v_mul_f32_e32 v101, v101, v134
	v_mul_f32_e32 v102, v102, v134
	v_mul_f32_e32 v103, v103, v134
	v_mul_f32_e32 v104, v104, v134
	v_mul_f32_e32 v105, v105, v134
	v_mul_f32_e32 v106, v106, v134
	v_mul_f32_e32 v107, v107, v134
	v_mul_f32_e32 v108, v108, v134
	v_mul_f32_e32 v109, v109, v134
	v_mul_f32_e32 v110, v110, v134
	v_mul_f32_e32 v111, v111, v134
	v_fma_f32 v96, v64, v96, v80
	v_fma_f32 v97, v65, v97, v81
	v_fma_f32 v98, v66, v98, v82
	v_fma_f32 v99, v67, v99, v83
	v_fma_f32 v100, v68, v100, v84
	v_fma_f32 v101, v69, v101, v85
	v_fma_f32 v102, v70, v102, v86
	v_fma_f32 v103, v71, v103, v87
	v_fma_f32 v104, v72, v104, v88
	v_fma_f32 v105, v73, v105, v89
	v_fma_f32 v106, v74, v106, v90
	v_fma_f32 v107, v75, v107, v91
	v_fma_f32 v108, v76, v108, v92
	v_fma_f32 v109, v77, v109, v93
	v_fma_f32 v110, v78, v110, v94
	v_fma_f32 v111, v79, v111, v95
	v_lshlrev_b32_e32 v162, 3, v16
	v_add_u32_e32 v162, 0xf000000, v162
	v_mov_b32_e32 v164, v133
	v_mov_b32_e32 v165, v134
	s_mov_b64 exec, 1
	global_store_dwordx2 v162, v[164:165], s[62:63]
	s_mov_b64 exec, -1
	v_ashrrev_i32_e32 v159, 31, v16
	v_mov_b32_e32 v158, v16
	v_lshlrev_b64 v[158:159], 11, v[158:159]
	v_lshl_add_u64 v[160:161], s[60:61], 0, v[158:159]
	v_mov_b32_e32 v158, v151
	v_mov_b32_e32 v159, 0
	v_lshl_add_u64 v[160:161], v[160:161], 0, v[158:159]
	v_cvt_pk_bf16_f32 v136, v96, v97
	v_cvt_pk_bf16_f32 v137, v98, v99
	v_cvt_pk_bf16_f32 v138, v100, v101
	v_cvt_pk_bf16_f32 v139, v102, v103
	v_cvt_pk_bf16_f32 v140, v104, v105
	v_cvt_pk_bf16_f32 v141, v106, v107
	v_cvt_pk_bf16_f32 v142, v108, v109
	v_cvt_pk_bf16_f32 v143, v110, v111
	global_store_dwordx2 v[160:161], v[136:137], off
	global_store_dwordx2 v[160:161], v[138:139], off offset:512
	global_store_dwordx2 v[160:161], v[140:141], off offset:1024
	global_store_dwordx2 v[160:161], v[142:143], off offset:1536
	v_mov_b32_e32 v16, v156
	v_mov_b32_e32 v152, v154
	v_mov_b32_e32 v153, v155
	s_add_i32 s10, s10, s96
	s_cmpk_lt_i32 s10, 0x800
	s_cbranch_scc0 .LBB0_1539
	s_add_i32 s99, s10, s96
	s_cmpk_lt_i32 s99, 0x800
	s_cselect_b32 s99, s2, 0
	v_add_u32_e32 v156, s99, v16
	v_ashrrev_i32_e32 v159, 31, v156
	v_mov_b32_e32 v158, v156
	v_lshlrev_b64 v[158:159], 12, v[158:159]
	v_lshl_add_u64 v[154:155], v[10:11], 0, v[158:159]
	global_load_dwordx4 v[96:99], v[154:155], off
	global_load_dwordx4 v[100:103], v[154:155], off offset:1024
	global_load_dwordx4 v[104:107], v[154:155], off offset:2048
	global_load_dwordx4 v[108:111], v[154:155], off offset:3072
	s_waitcnt vmcnt(9)
	v_add_f32_e32 v128, v112, v113
	v_add_f32_e32 v129, v116, v117
	v_add_f32_e32 v130, v120, v121
	v_add_f32_e32 v131, v124, v125
	v_add_f32_e32 v128, v114, v128
	v_add_f32_e32 v129, v118, v129
	v_add_f32_e32 v130, v122, v130
	v_add_f32_e32 v131, v126, v131
	v_add_f32_e32 v128, v115, v128
	v_add_f32_e32 v129, v119, v129
	v_add_f32_e32 v130, v123, v130
	v_add_f32_e32 v131, v127, v131
	v_add_f32_e32 v132, v128, v129
	v_add_f32_e32 v132, v132, v130
	v_add_f32_e32 v132, v132, v131
	s_nop 1
	v_add_f32_dpp v132, v132, v132 quad_perm:[1,0,3,2] row_mask:0xf bank_mask:0xf
	s_nop 1
	v_add_f32_dpp v132, v132, v132 quad_perm:[2,3,0,1] row_mask:0xf bank_mask:0xf
	s_nop 1
	v_add_f32_dpp v132, v132, v132 row_half_mirror row_mask:0xf bank_mask:0xf
	s_nop 1
	v_add_f32_dpp v132, v132, v132 row_mirror row_mask:0xf bank_mask:0xf
	ds_swizzle_b32 v147, v132 offset:0x401f
	s_waitcnt lgkmcnt(0)
	v_add_f32_e32 v132, v132, v147
	ds_bpermute_b32 v147, v149, v132
	s_waitcnt lgkmcnt(0)
	v_add_f32_e32 v132, v132, v147
	v_mul_f32_e32 v133, 0x3a800000, v132
	v_sub_f32_e32 v112, v112, v133
	v_sub_f32_e32 v113, v113, v133
	v_sub_f32_e32 v114, v114, v133
	v_sub_f32_e32 v115, v115, v133
	v_sub_f32_e32 v116, v116, v133
	v_sub_f32_e32 v117, v117, v133
	v_sub_f32_e32 v118, v118, v133
	v_sub_f32_e32 v119, v119, v133
	v_sub_f32_e32 v120, v120, v133
	v_sub_f32_e32 v121, v121, v133
	v_sub_f32_e32 v122, v122, v133
	v_sub_f32_e32 v123, v123, v133
	v_sub_f32_e32 v124, v124, v133
	v_sub_f32_e32 v125, v125, v133
	v_sub_f32_e32 v126, v126, v133
	v_sub_f32_e32 v127, v127, v133
	v_mul_f32_e32 v134, v112, v112
	v_mul_f32_e32 v135, v113, v113
	v_add_f32_e32 v134, v134, v135
	v_mul_f32_e32 v135, v114, v114
	v_add_f32_e32 v134, v135, v134
	v_mul_f32_e32 v135, v115, v115
	v_add_f32_e32 v134, v135, v134
	v_mul_f32_e32 v135, v116, v116
	v_add_f32_e32 v134, v135, v134
	v_mul_f32_e32 v135, v117, v117
	v_add_f32_e32 v134, v135, v134
	v_mul_f32_e32 v135, v118, v118
	v_add_f32_e32 v134, v135, v134
	v_mul_f32_e32 v135, v119, v119
	v_add_f32_e32 v134, v135, v134
	v_mul_f32_e32 v135, v120, v120
	v_add_f32_e32 v134, v135, v134
	v_mul_f32_e32 v135, v121, v121
	v_add_f32_e32 v134, v135, v134
	v_mul_f32_e32 v135, v122, v122
	v_add_f32_e32 v134, v135, v134
	v_mul_f32_e32 v135, v123, v123
	v_add_f32_e32 v134, v135, v134
	v_mul_f32_e32 v135, v124, v124
	v_add_f32_e32 v134, v135, v134
	v_mul_f32_e32 v135, v125, v125
	v_add_f32_e32 v134, v135, v134
	v_mul_f32_e32 v135, v126, v126
	v_add_f32_e32 v134, v135, v134
	v_mul_f32_e32 v135, v127, v127
	v_add_f32_e32 v134, v135, v134
	s_nop 1
	v_add_f32_dpp v134, v134, v134 quad_perm:[1,0,3,2] row_mask:0xf bank_mask:0xf
	s_nop 1
	v_add_f32_dpp v134, v134, v134 quad_perm:[2,3,0,1] row_mask:0xf bank_mask:0xf
	s_nop 1
	v_add_f32_dpp v134, v134, v134 row_half_mirror row_mask:0xf bank_mask:0xf
	s_nop 1
	v_add_f32_dpp v134, v134, v134 row_mirror row_mask:0xf bank_mask:0xf
	ds_swizzle_b32 v147, v134 offset:0x401f
	s_waitcnt lgkmcnt(0)
	v_add_f32_e32 v134, v134, v147
	ds_bpermute_b32 v147, v149, v134
	s_waitcnt lgkmcnt(0)
	v_add_f32_e32 v134, v134, v147
	v_fmamk_f32 v134, v134, 0x3a800000, v150
	v_rsq_f32_e32 v134, v134
	s_nop 0
	v_mul_f32_e32 v112, v112, v134
	v_mul_f32_e32 v113, v113, v134
	v_mul_f32_e32 v114, v114, v134
	v_mul_f32_e32 v115, v115, v134
	v_mul_f32_e32 v116, v116, v134
	v_mul_f32_e32 v117, v117, v134
	v_mul_f32_e32 v118, v118, v134
	v_mul_f32_e32 v119, v119, v134
	v_mul_f32_e32 v120, v120, v134
	v_mul_f32_e32 v121, v121, v134
	v_mul_f32_e32 v122, v122, v134
	v_mul_f32_e32 v123, v123, v134
	v_mul_f32_e32 v124, v124, v134
	v_mul_f32_e32 v125, v125, v134
	v_mul_f32_e32 v126, v126, v134
	v_mul_f32_e32 v127, v127, v134
	v_fma_f32 v112, v64, v112, v80
	v_fma_f32 v113, v65, v113, v81
	v_fma_f32 v114, v66, v114, v82
	v_fma_f32 v115, v67, v115, v83
	v_fma_f32 v116, v68, v116, v84
	v_fma_f32 v117, v69, v117, v85
	v_fma_f32 v118, v70, v118, v86
	v_fma_f32 v119, v71, v119, v87
	v_fma_f32 v120, v72, v120, v88
	v_fma_f32 v121, v73, v121, v89
	v_fma_f32 v122, v74, v122, v90
	v_fma_f32 v123, v75, v123, v91
	v_fma_f32 v124, v76, v124, v92
	v_fma_f32 v125, v77, v125, v93
	v_fma_f32 v126, v78, v126, v94
	v_fma_f32 v127, v79, v127, v95
	v_lshlrev_b32_e32 v162, 3, v16
	v_add_u32_e32 v162, 0xf000000, v162
	v_mov_b32_e32 v164, v133
	v_mov_b32_e32 v165, v134
	s_mov_b64 exec, 1
	global_store_dwordx2 v162, v[164:165], s[62:63]
	s_mov_b64 exec, -1
	v_ashrrev_i32_e32 v159, 31, v16
	v_mov_b32_e32 v158, v16
	v_lshlrev_b64 v[158:159], 11, v[158:159]
	v_lshl_add_u64 v[160:161], s[60:61], 0, v[158:159]
	v_mov_b32_e32 v158, v151
	v_mov_b32_e32 v159, 0
	v_lshl_add_u64 v[160:161], v[160:161], 0, v[158:159]
	v_cvt_pk_bf16_f32 v136, v112, v113
	v_cvt_pk_bf16_f32 v137, v114, v115
	v_cvt_pk_bf16_f32 v138, v116, v117
	v_cvt_pk_bf16_f32 v139, v118, v119
	v_cvt_pk_bf16_f32 v140, v120, v121
	v_cvt_pk_bf16_f32 v141, v122, v123
	v_cvt_pk_bf16_f32 v142, v124, v125
	v_cvt_pk_bf16_f32 v143, v126, v127
	global_store_dwordx2 v[160:161], v[136:137], off
	global_store_dwordx2 v[160:161], v[138:139], off offset:512
	global_store_dwordx2 v[160:161], v[140:141], off offset:1024
	global_store_dwordx2 v[160:161], v[142:143], off offset:1536
	v_mov_b32_e32 v16, v156
	v_mov_b32_e32 v152, v154
	v_mov_b32_e32 v153, v155
	s_add_i32 s10, s10, s96
	s_cmpk_lt_i32 s10, 0x800
	s_cbranch_scc0 .LBB0_1539
	s_branch .Lln_p10_loopA

.LBB0_1595:
	v_add_u32_e32 v2, s1, v168
	v_ashrrev_i32_e32 v3, 31, v2
	v_add_u32_e32 v4, 16, v2
	v_lshlrev_b64 v[2:3], 11, v[2:3]
	v_ashrrev_i32_e32 v5, 31, v4
	v_lshl_add_u64 v[2:3], v[156:157], 0, v[2:3]
	v_lshlrev_b64 v[6:7], 11, v[4:5]
	global_load_dwordx4 v[2:5], v[2:3], off
	v_lshl_add_u64 v[6:7], v[156:157], 0, v[6:7]
	global_load_dwordx4 v[114:117], v[6:7], off
	s_add_i32 s1, s1, 32
	s_cmpk_eq_i32 s1, 0x80
	s_waitcnt vmcnt(1)
	v_mfma_f32_32x32x16_bf16 v[176:191], v[2:5], v[130:133], 0
	v_mfma_f32_32x32x16_bf16 v[192:207], v[2:5], v[134:137], 0
	v_mfma_f32_32x32x16_bf16 v[208:223], v[2:5], v[138:141], 0
	v_mfma_f32_32x32x16_bf16 v[224:239], v[2:5], v[142:145], 0
	s_waitcnt vmcnt(0)
	v_mfma_f32_32x32x16_bf16 v[50:65], v[114:117], v[130:133], 0
	v_mfma_f32_32x32x16_bf16 v[66:81], v[114:117], v[134:137], 0
	v_mfma_f32_32x32x16_bf16 v[82:97], v[114:117], v[138:141], 0
	v_mfma_f32_32x32x16_bf16 v[98:113], v[114:117], v[142:145], 0
	s_nop 7
	v_fma_f32 v244, -v153, v35, v176
	v_fma_f32 v245, v153, v34, v192
	v_fma_f32 v246, -v155, v119, v208
	v_fma_f32 v247, v155, v118, v224
	v_fma_f32 v240, v152, v34, v244
	v_fma_f32 v241, v152, v35, v245
	v_fma_f32 v242, v154, v118, v246
	v_fma_f32 v243, v154, v119, v247
	v_fma_f32 v244, -v153, v241, v177
	v_fma_f32 v245, v153, v240, v193
	v_fma_f32 v246, -v155, v243, v209
	v_fma_f32 v247, v155, v242, v225
	v_fma_f32 v34, v152, v240, v244
	v_fma_f32 v35, v152, v241, v245
	v_fma_f32 v118, v154, v242, v246
	v_fma_f32 v119, v154, v243, v247
	v_fma_f32 v244, -v153, v35, v178
	v_fma_f32 v245, v153, v34, v194
	v_fma_f32 v246, -v155, v119, v210
	v_fma_f32 v247, v155, v118, v226
	v_fma_f32 v240, v152, v34, v244
	v_fma_f32 v241, v152, v35, v245
	v_fma_f32 v242, v154, v118, v246
	v_fma_f32 v243, v154, v119, v247
	v_fma_f32 v244, -v153, v241, v179
	v_fma_f32 v245, v153, v240, v195
	v_fma_f32 v246, -v155, v243, v211
	v_fma_f32 v247, v155, v242, v227
	v_fma_f32 v34, v152, v240, v244
	v_fma_f32 v35, v152, v241, v245
	v_fma_f32 v118, v154, v242, v246
	v_fma_f32 v119, v154, v243, v247
	v_fma_f32 v244, -v153, v35, v180
	v_fma_f32 v245, v153, v34, v196
	v_fma_f32 v246, -v155, v119, v212
	v_fma_f32 v247, v155, v118, v228
	v_fma_f32 v240, v152, v34, v244
	v_fma_f32 v241, v152, v35, v245
	v_fma_f32 v242, v154, v118, v246
	v_fma_f32 v243, v154, v119, v247
	v_fma_f32 v244, -v153, v241, v181
	v_fma_f32 v245, v153, v240, v197
	v_fma_f32 v246, -v155, v243, v213
	v_fma_f32 v247, v155, v242, v229
	v_fma_f32 v34, v152, v240, v244
	v_fma_f32 v35, v152, v241, v245
	v_fma_f32 v118, v154, v242, v246
	v_fma_f32 v119, v154, v243, v247
	v_fma_f32 v244, -v153, v35, v182
	v_fma_f32 v245, v153, v34, v198
	v_fma_f32 v246, -v155, v119, v214
	v_fma_f32 v247, v155, v118, v230
	v_fma_f32 v240, v152, v34, v244
	v_fma_f32 v241, v152, v35, v245
	v_fma_f32 v242, v154, v118, v246
	v_fma_f32 v243, v154, v119, v247
	v_fma_f32 v244, -v153, v241, v183
	v_fma_f32 v245, v153, v240, v199
	v_fma_f32 v246, -v155, v243, v215
	v_fma_f32 v247, v155, v242, v231
	v_fma_f32 v34, v152, v240, v244
	v_fma_f32 v35, v152, v241, v245
	v_fma_f32 v118, v154, v242, v246
	v_fma_f32 v119, v154, v243, v247
	v_fma_f32 v244, -v153, v35, v184
	v_fma_f32 v245, v153, v34, v200
	v_fma_f32 v246, -v155, v119, v216
	v_fma_f32 v247, v155, v118, v232
	v_fma_f32 v240, v152, v34, v244
	v_fma_f32 v241, v152, v35, v245
	v_fma_f32 v242, v154, v118, v246
	v_fma_f32 v243, v154, v119, v247
	v_fma_f32 v244, -v153, v241, v185
	v_fma_f32 v245, v153, v240, v201
	v_fma_f32 v246, -v155, v243, v217
	v_fma_f32 v247, v155, v242, v233
	v_fma_f32 v34, v152, v240, v244
	v_fma_f32 v35, v152, v241, v245
	v_fma_f32 v118, v154, v242, v246
	v_fma_f32 v119, v154, v243, v247
	v_fma_f32 v244, -v153, v35, v186
	v_fma_f32 v245, v153, v34, v202
	v_fma_f32 v246, -v155, v119, v218
	v_fma_f32 v247, v155, v118, v234
	v_fma_f32 v240, v152, v34, v244
	v_fma_f32 v241, v152, v35, v245
	v_fma_f32 v242, v154, v118, v246
	v_fma_f32 v243, v154, v119, v247
	v_fma_f32 v244, -v153, v241, v187
	v_fma_f32 v245, v153, v240, v203
	v_fma_f32 v246, -v155, v243, v219
	v_fma_f32 v247, v155, v242, v235
	v_fma_f32 v34, v152, v240, v244
	v_fma_f32 v35, v152, v241, v245
	v_fma_f32 v118, v154, v242, v246
	v_fma_f32 v119, v154, v243, v247
	v_fma_f32 v244, -v153, v35, v188
	v_fma_f32 v245, v153, v34, v204
	v_fma_f32 v246, -v155, v119, v220
	v_fma_f32 v247, v155, v118, v236
	v_fma_f32 v240, v152, v34, v244
	v_fma_f32 v241, v152, v35, v245
	v_fma_f32 v242, v154, v118, v246
	v_fma_f32 v243, v154, v119, v247
	v_fma_f32 v244, -v153, v241, v189
	v_fma_f32 v245, v153, v240, v205
	v_fma_f32 v246, -v155, v243, v221
	v_fma_f32 v247, v155, v242, v237
	v_fma_f32 v34, v152, v240, v244
	v_fma_f32 v35, v152, v241, v245
	v_fma_f32 v118, v154, v242, v246
	v_fma_f32 v119, v154, v243, v247
	v_fma_f32 v244, -v153, v35, v190
	v_fma_f32 v245, v153, v34, v206
	v_fma_f32 v246, -v155, v119, v222
	v_fma_f32 v247, v155, v118, v238
	v_fma_f32 v240, v152, v34, v244
	v_fma_f32 v241, v152, v35, v245
	v_fma_f32 v242, v154, v118, v246
	v_fma_f32 v243, v154, v119, v247
	v_fma_f32 v244, -v153, v241, v191
	v_fma_f32 v245, v153, v240, v207
	v_fma_f32 v246, -v155, v243, v223
	v_fma_f32 v247, v155, v242, v239
	v_fma_f32 v34, v152, v240, v244
	v_fma_f32 v35, v152, v241, v245
	v_fma_f32 v118, v154, v242, v246
	v_fma_f32 v119, v154, v243, v247
	v_fma_f32 v244, -v153, v35, v50
	v_fma_f32 v245, v153, v34, v66
	v_fma_f32 v246, -v155, v119, v82
	v_fma_f32 v247, v155, v118, v98
	v_fma_f32 v240, v152, v34, v244
	v_fma_f32 v241, v152, v35, v245
	v_fma_f32 v242, v154, v118, v246
	v_fma_f32 v243, v154, v119, v247
	v_fma_f32 v244, -v153, v241, v51
	v_fma_f32 v245, v153, v240, v67
	v_fma_f32 v246, -v155, v243, v83
	v_fma_f32 v247, v155, v242, v99
	v_fma_f32 v34, v152, v240, v244
	v_fma_f32 v35, v152, v241, v245
	v_fma_f32 v118, v154, v242, v246
	v_fma_f32 v119, v154, v243, v247
	v_fma_f32 v244, -v153, v35, v52
	v_fma_f32 v245, v153, v34, v68
	v_fma_f32 v246, -v155, v119, v84
	v_fma_f32 v247, v155, v118, v100
	v_fma_f32 v240, v152, v34, v244
	v_fma_f32 v241, v152, v35, v245
	v_fma_f32 v242, v154, v118, v246
	v_fma_f32 v243, v154, v119, v247
	v_fma_f32 v244, -v153, v241, v53
	v_fma_f32 v245, v153, v240, v69
	v_fma_f32 v246, -v155, v243, v85
	v_fma_f32 v247, v155, v242, v101
	v_fma_f32 v34, v152, v240, v244
	v_fma_f32 v35, v152, v241, v245
	v_fma_f32 v118, v154, v242, v246
	v_fma_f32 v119, v154, v243, v247
	v_fma_f32 v244, -v153, v35, v54
	v_fma_f32 v245, v153, v34, v70
	v_fma_f32 v246, -v155, v119, v86
	v_fma_f32 v247, v155, v118, v102
	v_fma_f32 v240, v152, v34, v244
	v_fma_f32 v241, v152, v35, v245
	v_fma_f32 v242, v154, v118, v246
	v_fma_f32 v243, v154, v119, v247
	v_fma_f32 v244, -v153, v241, v55
	v_fma_f32 v245, v153, v240, v71
	v_fma_f32 v246, -v155, v243, v87
	v_fma_f32 v247, v155, v242, v103
	v_fma_f32 v34, v152, v240, v244
	v_fma_f32 v35, v152, v241, v245
	v_fma_f32 v118, v154, v242, v246
	v_fma_f32 v119, v154, v243, v247
	v_fma_f32 v244, -v153, v35, v56
	v_fma_f32 v245, v153, v34, v72
	v_fma_f32 v246, -v155, v119, v88
	v_fma_f32 v247, v155, v118, v104
	v_fma_f32 v240, v152, v34, v244
	v_fma_f32 v241, v152, v35, v245
	v_fma_f32 v242, v154, v118, v246
	v_fma_f32 v243, v154, v119, v247
	v_fma_f32 v244, -v153, v241, v57
	v_fma_f32 v245, v153, v240, v73
	v_fma_f32 v246, -v155, v243, v89
	v_fma_f32 v247, v155, v242, v105
	v_fma_f32 v34, v152, v240, v244
	v_fma_f32 v35, v152, v241, v245
	v_fma_f32 v118, v154, v242, v246
	v_fma_f32 v119, v154, v243, v247
	v_fma_f32 v244, -v153, v35, v58
	v_fma_f32 v245, v153, v34, v74
	v_fma_f32 v246, -v155, v119, v90
	v_fma_f32 v247, v155, v118, v106
	v_fma_f32 v240, v152, v34, v244
	v_fma_f32 v241, v152, v35, v245
	v_fma_f32 v242, v154, v118, v246
	v_fma_f32 v243, v154, v119, v247
	v_fma_f32 v244, -v153, v241, v59
	v_fma_f32 v245, v153, v240, v75
	v_fma_f32 v246, -v155, v243, v91
	v_fma_f32 v247, v155, v242, v107
	v_fma_f32 v34, v152, v240, v244
	v_fma_f32 v35, v152, v241, v245
	v_fma_f32 v118, v154, v242, v246
	v_fma_f32 v119, v154, v243, v247
	v_fma_f32 v244, -v153, v35, v60
	v_fma_f32 v245, v153, v34, v76
	v_fma_f32 v246, -v155, v119, v92
	v_fma_f32 v247, v155, v118, v108
	v_fma_f32 v240, v152, v34, v244
	v_fma_f32 v241, v152, v35, v245
	v_fma_f32 v242, v154, v118, v246
	v_fma_f32 v243, v154, v119, v247
	v_fma_f32 v244, -v153, v241, v61
	v_fma_f32 v245, v153, v240, v77
	v_fma_f32 v246, -v155, v243, v93
	v_fma_f32 v247, v155, v242, v109
	v_fma_f32 v34, v152, v240, v244
	v_fma_f32 v35, v152, v241, v245
	v_fma_f32 v118, v154, v242, v246
	v_fma_f32 v119, v154, v243, v247
	v_fma_f32 v244, -v153, v35, v62
	v_fma_f32 v245, v153, v34, v78
	v_fma_f32 v246, -v155, v119, v94
	v_fma_f32 v247, v155, v118, v110
	v_fma_f32 v240, v152, v34, v244
	v_fma_f32 v241, v152, v35, v245
	v_fma_f32 v242, v154, v118, v246
	v_fma_f32 v243, v154, v119, v247
	v_fma_f32 v244, -v153, v241, v63
	v_fma_f32 v245, v153, v240, v79
	v_fma_f32 v246, -v155, v243, v95
	v_fma_f32 v247, v155, v242, v111
	v_fma_f32 v34, v152, v240, v244
	v_fma_f32 v35, v152, v241, v245
	v_fma_f32 v118, v154, v242, v246
	v_fma_f32 v119, v154, v243, v247
	v_fma_f32 v244, -v153, v35, v64
	v_fma_f32 v245, v153, v34, v80
	v_fma_f32 v246, -v155, v119, v96
	v_fma_f32 v247, v155, v118, v112
	v_fma_f32 v240, v152, v34, v244
	v_fma_f32 v241, v152, v35, v245
	v_fma_f32 v242, v154, v118, v246
	v_fma_f32 v243, v154, v119, v247
	v_fma_f32 v244, -v153, v241, v65
	v_fma_f32 v245, v153, v240, v81
	v_fma_f32 v246, -v155, v243, v97
	v_fma_f32 v247, v155, v242, v113
	v_fma_f32 v34, v152, v240, v244
	v_fma_f32 v35, v152, v241, v245
	v_fma_f32 v118, v154, v242, v246
	v_fma_f32 v119, v154, v243, v247
	s_cbranch_scc0 .LBB0_1595
	s_nop 0
	s_nop 0
	s_nop 0
	s_nop 0
	s_nop 0
	s_nop 0
	s_nop 0
	s_nop 0
	s_nop 0
	s_nop 0
	s_nop 0
	s_nop 0
	s_nop 0
	s_nop 0
	v_lshlrev_b32_e32 v2, 7, v167
	v_or3_b32 v2, v2, v163, v166
	v_ashrrev_i32_e32 v3, 31, v2
	v_lshlrev_b64 v[2:3], 9, v[2:3]
	s_add_i32 s0, s0, s96
	v_lshl_add_u64 v[2:3], v[150:151], 0, v[2:3]
	s_cmpk_gt_i32 s0, 0x1ff
	global_store_dwordx2 v[2:3], v[34:35], off
	global_store_dwordx2 v[2:3], v[118:119], off offset:256
	s_cbranch_scc0 .LBB0_1594

.LBB0_1714:
	v_add_u32_e32 v140, s13, v100
	v_lshlrev_b32_e32 v142, 2, v112
	v_lshl_or_b32 v141, v140, 12, v142
	v_add_u32_e32 v143, 0x1000, v141
	v_add_u32_e32 v144, 0x3000, v141
	v_add_u32_e32 v145, 0x81000, v141
	v_add_u32_e32 v146, 0x83000, v141
	v_lshlrev_b32_e32 v147, 3, v140
	v_readlane_b32 s98, v253, 18
	v_readlane_b32 s99, v253, 19
	s_nop 4
	global_load_dword v138, v142, s[98:99]
	v_readlane_b32 s98, v253, 20
	v_readlane_b32 s99, v253, 21
	s_nop 4
	global_load_dword v139, v142, s[98:99]
	s_add_u32 s98, s62, 0xf000000
	s_addc_u32 s99, s63, 0
	global_load_dwordx4 v[148:151], v147, s[98:99]
	global_load_dwordx4 v[152:155], v147, s[98:99] offset:16
	global_load_dwordx4 v[244:247], v147, s[98:99] offset:1024
	global_load_dwordx4 v[248:251], v147, s[98:99] offset:1040
	global_load_dword v156, v143, s[66:67] offset:-4096
	global_load_dword v157, v143, s[66:67]
	global_load_dword v158, v144, s[66:67] offset:-4096
	global_load_dword v159, v144, s[66:67]
	global_load_dword v160, v145, s[66:67] offset:-4096
	global_load_dword v161, v145, s[66:67]
	global_load_dword v162, v146, s[66:67] offset:-4096
	global_load_dword v163, v146, s[66:67]
	s_waitcnt lgkmcnt(0)
	v_mfma_f32_32x32x16_bf16 v[164:179], v[18:21], v[64:67], 0
	v_mfma_f32_32x32x16_bf16 v[180:195], v[18:21], v[68:71], 0
	v_mfma_f32_32x32x16_bf16 v[196:211], v[18:21], v[72:75], 0
	v_mfma_f32_32x32x16_bf16 v[212:227], v[18:21], v[76:79], 0
	v_add_u32_e32 v228, 0x200, v129
	v_add_u32_e32 v229, 0x400, v129
	v_add_u32_e32 v230, 0x600, v129
	v_add_u32_e32 v231, 0x800, v129
	v_add_u32_e32 v232, 0xa00, v129
	v_add_u32_e32 v233, 0xc00, v129
	v_add_u32_e32 v234, 0xe00, v129
	s_nop 15
	s_nop 3
	v_fma_f32 v236, -v109, v49, v164
	v_fma_f32 v237, v109, v48, v180
	v_fma_f32 v238, -v111, v121, v196
	v_fma_f32 v239, v111, v120, v212
	v_fma_f32 v48, v108, v48, v236
	v_fma_f32 v49, v108, v49, v237
	v_fma_f32 v120, v110, v120, v238
	v_fma_f32 v121, v110, v121, v239
	v_cvt_pk_bf16_f32 v240, v48, v49
	v_cvt_pk_bf16_f32 v241, v120, v121
	ds_write2_b32 v129, v240, v241 offset0:0 offset1:32
	v_fma_f32 v236, -v109, v49, v165
	v_fma_f32 v237, v109, v48, v181
	v_fma_f32 v238, -v111, v121, v197
	v_fma_f32 v239, v111, v120, v213
	v_fma_f32 v48, v108, v48, v236
	v_fma_f32 v49, v108, v49, v237
	v_fma_f32 v120, v110, v120, v238
	v_fma_f32 v121, v110, v121, v239
	v_cvt_pk_bf16_f32 v242, v48, v49
	v_cvt_pk_bf16_f32 v243, v120, v121
	ds_write2_b32 v129, v242, v243 offset0:68 offset1:100
	v_fma_f32 v236, -v109, v49, v166
	v_fma_f32 v237, v109, v48, v182
	v_fma_f32 v238, -v111, v121, v198
	v_fma_f32 v239, v111, v120, v214
	v_fma_f32 v48, v108, v48, v236
	v_fma_f32 v49, v108, v49, v237
	v_fma_f32 v120, v110, v120, v238
	v_fma_f32 v121, v110, v121, v239
	v_cvt_pk_bf16_f32 v240, v48, v49
	v_cvt_pk_bf16_f32 v241, v120, v121
	ds_write2_b32 v228, v240, v241 offset0:8 offset1:40
	v_fma_f32 v236, -v109, v49, v167
	v_fma_f32 v237, v109, v48, v183
	v_fma_f32 v238, -v111, v121, v199
	v_fma_f32 v239, v111, v120, v215
	v_fma_f32 v48, v108, v48, v236
	v_fma_f32 v49, v108, v49, v237
	v_fma_f32 v120, v110, v120, v238
	v_fma_f32 v121, v110, v121, v239
	v_cvt_pk_bf16_f32 v242, v48, v49
	v_cvt_pk_bf16_f32 v243, v120, v121
	ds_write2_b32 v228, v242, v243 offset0:76 offset1:108
	v_fma_f32 v236, -v109, v49, v168
	v_fma_f32 v237, v109, v48, v184
	v_fma_f32 v238, -v111, v121, v200
	v_fma_f32 v239, v111, v120, v216
	v_fma_f32 v48, v108, v48, v236
	v_fma_f32 v49, v108, v49, v237
	v_fma_f32 v120, v110, v120, v238
	v_fma_f32 v121, v110, v121, v239
	v_cvt_pk_bf16_f32 v240, v48, v49
	v_cvt_pk_bf16_f32 v241, v120, v121
	ds_write2_b32 v229, v240, v241 offset0:16 offset1:48
	v_fma_f32 v236, -v109, v49, v169
	v_fma_f32 v237, v109, v48, v185
	v_fma_f32 v238, -v111, v121, v201
	v_fma_f32 v239, v111, v120, v217
	v_fma_f32 v48, v108, v48, v236
	v_fma_f32 v49, v108, v49, v237
	v_fma_f32 v120, v110, v120, v238
	v_fma_f32 v121, v110, v121, v239
	v_cvt_pk_bf16_f32 v242, v48, v49
	v_cvt_pk_bf16_f32 v243, v120, v121
	ds_write2_b32 v229, v242, v243 offset0:84 offset1:116
	v_fma_f32 v236, -v109, v49, v170
	v_fma_f32 v237, v109, v48, v186
	v_fma_f32 v238, -v111, v121, v202
	v_fma_f32 v239, v111, v120, v218
	v_fma_f32 v48, v108, v48, v236
	v_fma_f32 v49, v108, v49, v237
	v_fma_f32 v120, v110, v120, v238
	v_fma_f32 v121, v110, v121, v239
	v_cvt_pk_bf16_f32 v240, v48, v49
	v_cvt_pk_bf16_f32 v241, v120, v121
	ds_write2_b32 v230, v240, v241 offset0:24 offset1:56
	v_fma_f32 v236, -v109, v49, v171
	v_fma_f32 v237, v109, v48, v187
	v_fma_f32 v238, -v111, v121, v203
	v_fma_f32 v239, v111, v120, v219
	v_fma_f32 v48, v108, v48, v236
	v_fma_f32 v49, v108, v49, v237
	v_fma_f32 v120, v110, v120, v238
	v_fma_f32 v121, v110, v121, v239
	v_cvt_pk_bf16_f32 v242, v48, v49
	v_cvt_pk_bf16_f32 v243, v120, v121
	ds_write2_b32 v230, v242, v243 offset0:92 offset1:124
	v_fma_f32 v236, -v109, v49, v172
	v_fma_f32 v237, v109, v48, v188
	v_fma_f32 v238, -v111, v121, v204
	v_fma_f32 v239, v111, v120, v220
	v_fma_f32 v48, v108, v48, v236
	v_fma_f32 v49, v108, v49, v237
	v_fma_f32 v120, v110, v120, v238
	v_fma_f32 v121, v110, v121, v239
	v_cvt_pk_bf16_f32 v240, v48, v49
	v_cvt_pk_bf16_f32 v241, v120, v121
	ds_write2_b32 v231, v240, v241 offset0:32 offset1:64
	v_fma_f32 v236, -v109, v49, v173
	v_fma_f32 v237, v109, v48, v189
	v_fma_f32 v238, -v111, v121, v205
	v_fma_f32 v239, v111, v120, v221
	v_fma_f32 v48, v108, v48, v236
	v_fma_f32 v49, v108, v49, v237
	v_fma_f32 v120, v110, v120, v238
	v_fma_f32 v121, v110, v121, v239
	v_cvt_pk_bf16_f32 v242, v48, v49
	v_cvt_pk_bf16_f32 v243, v120, v121
	ds_write2_b32 v231, v242, v243 offset0:100 offset1:132
	v_fma_f32 v236, -v109, v49, v174
	v_fma_f32 v237, v109, v48, v190
	v_fma_f32 v238, -v111, v121, v206
	v_fma_f32 v239, v111, v120, v222
	v_fma_f32 v48, v108, v48, v236
	v_fma_f32 v49, v108, v49, v237
	v_fma_f32 v120, v110, v120, v238
	v_fma_f32 v121, v110, v121, v239
	v_cvt_pk_bf16_f32 v240, v48, v49
	v_cvt_pk_bf16_f32 v241, v120, v121
	ds_write2_b32 v232, v240, v241 offset0:40 offset1:72
	v_fma_f32 v236, -v109, v49, v175
	v_fma_f32 v237, v109, v48, v191
	v_fma_f32 v238, -v111, v121, v207
	v_fma_f32 v239, v111, v120, v223
	v_fma_f32 v48, v108, v48, v236
	v_fma_f32 v49, v108, v49, v237
	v_fma_f32 v120, v110, v120, v238
	v_fma_f32 v121, v110, v121, v239
	v_cvt_pk_bf16_f32 v242, v48, v49
	v_cvt_pk_bf16_f32 v243, v120, v121
	ds_write2_b32 v232, v242, v243 offset0:108 offset1:140
	v_fma_f32 v236, -v109, v49, v176
	v_fma_f32 v237, v109, v48, v192
	v_fma_f32 v238, -v111, v121, v208
	v_fma_f32 v239, v111, v120, v224
	v_fma_f32 v48, v108, v48, v236
	v_fma_f32 v49, v108, v49, v237
	v_fma_f32 v120, v110, v120, v238
	v_fma_f32 v121, v110, v121, v239
	v_cvt_pk_bf16_f32 v240, v48, v49
	v_cvt_pk_bf16_f32 v241, v120, v121
	ds_write2_b32 v233, v240, v241 offset0:48 offset1:80
	v_fma_f32 v236, -v109, v49, v177
	v_fma_f32 v237, v109, v48, v193
	v_fma_f32 v238, -v111, v121, v209
	v_fma_f32 v239, v111, v120, v225
	v_fma_f32 v48, v108, v48, v236
	v_fma_f32 v49, v108, v49, v237
	v_fma_f32 v120, v110, v120, v238
	v_fma_f32 v121, v110, v121, v239
	v_cvt_pk_bf16_f32 v242, v48, v49
	v_cvt_pk_bf16_f32 v243, v120, v121
	ds_write2_b32 v233, v242, v243 offset0:116 offset1:148
	v_fma_f32 v236, -v109, v49, v178
	v_fma_f32 v237, v109, v48, v194
	v_fma_f32 v238, -v111, v121, v210
	v_fma_f32 v239, v111, v120, v226
	v_fma_f32 v48, v108, v48, v236
	v_fma_f32 v49, v108, v49, v237
	v_fma_f32 v120, v110, v120, v238
	v_fma_f32 v121, v110, v121, v239
	v_cvt_pk_bf16_f32 v240, v48, v49
	v_cvt_pk_bf16_f32 v241, v120, v121
	ds_write2_b32 v234, v240, v241 offset0:56 offset1:88
	v_fma_f32 v236, -v109, v49, v179
	v_fma_f32 v237, v109, v48, v195
	v_fma_f32 v238, -v111, v121, v211
	v_fma_f32 v239, v111, v120, v227
	v_fma_f32 v48, v108, v48, v236
	v_fma_f32 v49, v108, v49, v237
	v_fma_f32 v120, v110, v120, v238
	v_fma_f32 v121, v110, v121, v239
	v_cvt_pk_bf16_f32 v242, v48, v49
	v_cvt_pk_bf16_f32 v243, v120, v121
	ds_write2_b32 v234, v242, v243 offset0:124 offset1:156
	v_add_u32_e32 v14, s13, v100
	v_ashrrev_i32_e32 v15, 31, v14
	v_add_u32_e32 v10, 1, v14
	v_ashrrev_i32_e32 v11, 31, v10
	v_lshlrev_b64 v[18:19], 10, v[10:11]
	v_lshlrev_b64 v[16:17], 10, v[14:15]
	v_or_b32_e32 v16, v16, v112
	s_waitcnt lgkmcnt(0)
	s_nop 0
	s_nop 0
	s_nop 0
	s_nop 0
	s_nop 0
	s_nop 0
	s_nop 0
	s_nop 0
	s_nop 0
	s_nop 0
	s_nop 0
	v_lshl_add_u64 v[2:3], v[16:17], 2, s[66:67]
	ds_read_b128 v[2:5], v130
	ds_read_b128 v[6:9], v130 offset:64
	v_or_b32_e32 v18, v18, v112
	s_waitcnt lgkmcnt(1)
	v_mfma_f32_16x16x32_bf16 v[2:5], v[2:5], v[80:83], 0
	v_lshl_add_u64 v[10:11], v[18:19], 2, s[66:67]
	s_add_i32 s13, s13, 16
	s_waitcnt lgkmcnt(0)
	v_mfma_f32_16x16x32_bf16 v[2:5], v[6:9], v[84:87], v[2:5]
	ds_read_b128 v[6:9], v130 offset:128
	ds_read_b128 v[10:13], v130 offset:192
	s_cmpk_eq_i32 s13, 0x80
	s_waitcnt lgkmcnt(1)
	v_mfma_f32_16x16x32_bf16 v[2:5], v[6:9], v[88:91], v[2:5]
	v_add_u32_e32 v6, 2, v14
	v_ashrrev_i32_e32 v7, 31, v6
	v_lshlrev_b64 v[22:23], 10, v[6:7]
	v_or_b32_e32 v22, v22, v112
	v_lshl_add_u64 v[6:7], v[22:23], 2, s[66:67]
	v_add_u32_e32 v6, 3, v14
	v_ashrrev_i32_e32 v7, 31, v6
	v_lshlrev_b64 v[24:25], 10, v[6:7]
	v_or_b32_e32 v24, v24, v112
	v_lshl_add_u64 v[6:7], v[24:25], 2, s[66:67]
	v_add_u32_e32 v6, 0x80, v14
	s_waitcnt lgkmcnt(0)
	v_mfma_f32_16x16x32_bf16 v[2:5], v[10:13], v[92:95], v[2:5]
	v_ashrrev_i32_e32 v7, 31, v6
	v_add_u32_e32 v8, 0x81, v14
	v_add_u32_e32 v10, 0x82, v14
	v_add_u32_e32 v12, 0x83, v14
	v_lshlrev_b64 v[26:27], 10, v[6:7]
	v_ashrrev_i32_e32 v9, 31, v8
	v_ashrrev_i32_e32 v11, 31, v10
	v_ashrrev_i32_e32 v13, 31, v12
	v_or_b32_e32 v26, v26, v112
	v_lshlrev_b64 v[28:29], 10, v[8:9]
	v_lshlrev_b64 v[30:31], 10, v[10:11]
	v_lshlrev_b64 v[32:33], 10, v[12:13]
	v_lshl_add_u64 v[6:7], v[26:27], 2, s[66:67]
	v_or_b32_e32 v28, v28, v112
	v_or_b32_e32 v30, v30, v112
	v_or_b32_e32 v32, v32, v112
	v_lshl_add_u64 v[8:9], v[28:29], 2, s[66:67]
	v_lshl_add_u64 v[10:11], v[30:31], 2, s[66:67]
	v_lshl_add_u64 v[12:13], v[32:33], 2, s[66:67]
	ds_read_b128 v[10:13], v130 offset:4416
	s_waitcnt vmcnt(7)
	v_sub_f32_e32 v156, v156, v148
	v_mul_f32_e32 v156, v156, v149
	v_fma_f32 v156, v138, v156, v139
	v_fma_f32 v2, v131, v156, v2
	v_mul_f32_e32 v6, 0x3d372713, v2
	v_mul_f32_e32 v6, v2, v6
	v_fma_f32 v6, v2, v6, v2
	v_mul_f32_e32 v6, 0x3f4c422a, v6
	v_add_f32_e32 v6, v6, v6
	v_mul_f32_e32 v6, 0x3fb8aa3b, v6
	v_exp_f32_e32 v6, v6
	s_waitcnt vmcnt(6)
	v_sub_f32_e32 v157, v157, v150
	v_mul_f32_e32 v157, v157, v151
	v_fma_f32 v157, v138, v157, v139
	v_fma_f32 v7, v131, v157, v3
	v_mul_f32_e32 v3, 0x3d372713, v7
	v_mul_f32_e32 v3, v7, v3
	v_fma_f32 v3, v7, v3, v7
	v_add_f32_e32 v6, 1.0, v6
	v_mul_f32_e32 v3, 0x3f4c422a, v3
	v_rcp_f32_e32 v6, v6
	v_add_f32_e32 v3, v3, v3
	v_mul_f32_e32 v3, 0x3fb8aa3b, v3
	v_exp_f32_e32 v3, v3
	v_fma_f32 v6, v6, -2.0, 1.0
	v_mul_f32_e32 v2, 0.5, v2
	v_add_f32_e32 v6, 1.0, v6
	v_mul_f32_e32 v2, v2, v6
	v_add_f32_e32 v3, 1.0, v3
	v_rcp_f32_e32 v6, v3
	v_cvt_pk_bf16_f32 v8, v2, s0
	v_lshl_add_u64 v[2:3], v[16:17], 1, s[68:69]
	s_waitcnt vmcnt(5)
	v_sub_f32_e32 v158, v158, v152
	v_mul_f32_e32 v158, v158, v153
	v_fma_f32 v158, v138, v158, v139
	v_fma_f32 v4, v131, v158, v4
	global_store_short v[2:3], v8, off
	v_mul_f32_e32 v3, 0x3d372713, v4
	v_mul_f32_e32 v3, v4, v3
	v_fma_f32 v3, v4, v3, v4
	v_mul_f32_e32 v3, 0x3f4c422a, v3
	v_add_f32_e32 v3, v3, v3
	v_mul_f32_e32 v3, 0x3fb8aa3b, v3
	v_exp_f32_e32 v3, v3
	v_fma_f32 v2, v6, -2.0, 1.0
	v_mul_f32_e32 v6, 0.5, v7
	v_add_f32_e32 v2, 1.0, v2
	v_add_f32_e32 v3, 1.0, v3
	v_mul_f32_e32 v2, v6, v2
	v_rcp_f32_e32 v6, v3
	v_cvt_pk_bf16_f32 v7, v2, s0
	v_lshl_add_u64 v[2:3], v[18:19], 1, s[68:69]
	global_store_short v[2:3], v7, off
	v_fma_f32 v2, v6, -2.0, 1.0
	ds_read_b128 v[6:9], v130 offset:4352
	ds_read_b128 v[14:17], v130 offset:4480
	ds_read_b128 v[18:21], v130 offset:4544
	s_waitcnt lgkmcnt(2)
	v_mfma_f32_16x16x32_bf16 v[6:9], v[6:9], v[80:83], 0
	v_mul_f32_e32 v3, 0.5, v4
	v_add_f32_e32 v2, 1.0, v2
	s_waitcnt vmcnt(6)
	v_sub_f32_e32 v159, v159, v154
	v_mul_f32_e32 v159, v159, v155
	v_fma_f32 v159, v138, v159, v139
	v_fmac_f32_e32 v5, v131, v159
	v_mul_f32_e32 v2, v3, v2
	v_mul_f32_e32 v3, 0x3d372713, v5
	v_mfma_f32_16x16x32_bf16 v[6:9], v[10:13], v[84:87], v[6:9]
	v_mul_f32_e32 v3, v5, v3
	v_fma_f32 v3, v5, v3, v5
	v_mul_f32_e32 v3, 0x3f4c422a, v3
	v_add_f32_e32 v3, v3, v3
	s_waitcnt lgkmcnt(1)
	v_mfma_f32_16x16x32_bf16 v[6:9], v[14:17], v[88:91], v[6:9]
	v_mul_f32_e32 v3, 0x3fb8aa3b, v3
	v_exp_f32_e32 v3, v3
	v_cvt_pk_bf16_f32 v4, v2, s0
	s_waitcnt lgkmcnt(0)
	v_mfma_f32_16x16x32_bf16 v[6:9], v[18:21], v[92:95], v[6:9]
	v_mul_f32_e32 v5, 0.5, v5
	v_add_f32_e32 v2, 1.0, v3
	v_rcp_f32_e32 v10, v2
	v_lshl_add_u64 v[2:3], v[22:23], 1, s[68:69]
	global_store_short v[2:3], v4, off
	s_waitcnt vmcnt(6)
	s_nop 1
	v_sub_f32_e32 v160, v160, v244
	v_mul_f32_e32 v160, v160, v245
	v_fma_f32 v160, v138, v160, v139
	v_fma_f32 v4, v131, v160, v6
	v_mul_f32_e32 v3, 0x3d372713, v4
	v_mul_f32_e32 v3, v4, v3
	v_fma_f32 v3, v4, v3, v4
	v_mul_f32_e32 v3, 0x3f4c422a, v3
	v_add_f32_e32 v3, v3, v3
	v_mul_f32_e32 v3, 0x3fb8aa3b, v3
	v_exp_f32_e32 v3, v3
	v_fma_f32 v2, v10, -2.0, 1.0
	v_add_f32_e32 v2, 1.0, v2
	v_mul_f32_e32 v2, v5, v2
	v_add_f32_e32 v3, 1.0, v3
	v_rcp_f32_e32 v5, v3
	v_cvt_pk_bf16_f32 v6, v2, s0
	v_lshl_add_u64 v[2:3], v[24:25], 1, s[68:69]
	global_store_short v[2:3], v6, off
	v_fma_f32 v2, v5, -2.0, 1.0
	s_waitcnt vmcnt(6)
	v_sub_f32_e32 v161, v161, v246
	v_mul_f32_e32 v161, v161, v247
	v_fma_f32 v161, v138, v161, v139
	v_fma_f32 v5, v131, v161, v7
	v_mul_f32_e32 v3, 0x3d372713, v5
	v_mul_f32_e32 v3, v5, v3
	v_fma_f32 v3, v5, v3, v5
	v_mul_f32_e32 v3, 0x3f4c422a, v3
	v_add_f32_e32 v3, v3, v3
	v_mul_f32_e32 v3, 0x3fb8aa3b, v3
	v_exp_f32_e32 v3, v3
	v_mul_f32_e32 v4, 0.5, v4
	v_add_f32_e32 v2, 1.0, v2
	v_mul_f32_e32 v2, v4, v2
	v_add_f32_e32 v3, 1.0, v3
	v_rcp_f32_e32 v4, v3
	v_cvt_pk_bf16_f32 v6, v2, s0
	v_lshl_add_u64 v[2:3], v[26:27], 1, s[68:69]
	global_store_short v[2:3], v6, off
	v_fma_f32 v2, v4, -2.0, 1.0
	s_waitcnt vmcnt(6)
	v_sub_f32_e32 v162, v162, v248
	v_mul_f32_e32 v162, v162, v249
	v_fma_f32 v162, v138, v162, v139
	v_fma_f32 v4, v131, v162, v8
	v_mul_f32_e32 v3, 0x3d372713, v4
	v_mul_f32_e32 v3, v4, v3
	v_fma_f32 v3, v4, v3, v4
	v_mul_f32_e32 v3, 0x3f4c422a, v3
	v_add_f32_e32 v3, v3, v3
	v_mul_f32_e32 v3, 0x3fb8aa3b, v3
	v_exp_f32_e32 v3, v3
	v_mul_f32_e32 v5, 0.5, v5
	v_add_f32_e32 v2, 1.0, v2
	v_mul_f32_e32 v2, v5, v2
	v_add_f32_e32 v3, 1.0, v3
	v_rcp_f32_e32 v5, v3
	v_cvt_pk_bf16_f32 v6, v2, s0
	v_lshl_add_u64 v[2:3], v[28:29], 1, s[68:69]
	s_waitcnt vmcnt(5)
	v_sub_f32_e32 v163, v163, v250
	v_mul_f32_e32 v163, v163, v251
	v_fma_f32 v163, v138, v163, v139
	v_fmac_f32_e32 v9, v131, v163
	global_store_short v[2:3], v6, off
	v_mul_f32_e32 v3, 0x3d372713, v9
	v_mul_f32_e32 v3, v9, v3
	v_fma_f32 v3, v9, v3, v9
	v_mul_f32_e32 v3, 0x3f4c422a, v3
	v_add_f32_e32 v3, v3, v3
	v_mul_f32_e32 v3, 0x3fb8aa3b, v3
	v_exp_f32_e32 v3, v3
	v_fma_f32 v2, v5, -2.0, 1.0
	v_mul_f32_e32 v4, 0.5, v4
	v_add_f32_e32 v2, 1.0, v2
	v_add_f32_e32 v3, 1.0, v3
	v_mul_f32_e32 v2, v4, v2
	v_rcp_f32_e32 v4, v3
	v_cvt_pk_bf16_f32 v5, v2, s0
	v_lshl_add_u64 v[2:3], v[30:31], 1, s[68:69]
	global_store_short v[2:3], v5, off
	v_fma_f32 v2, v4, -2.0, 1.0
	v_mul_f32_e32 v3, 0.5, v9
	v_add_f32_e32 v2, 1.0, v2
	v_mul_f32_e32 v2, v3, v2
	v_mov_b64_e32 v[18:19], v[96:97]
	v_cvt_pk_bf16_f32 v4, v2, s0
	v_lshl_add_u64 v[2:3], v[32:33], 1, s[68:69]
	v_mov_b64_e32 v[20:21], v[98:99]
	global_store_short v[2:3], v4, off
	s_cbranch_scc1 .LBB0_1712

.LBB0_1772:
	v_and_b32_e32 v246, 7, v0
	v_lshlrev_b32_e32 v246, 5, v246
	s_lshl_b32 s98, s75, 9
	v_mov_b32_e32 v247, 0
	v_add_u32_e32 v246, s98, v246
	v_lshrrev_b32_e32 v244, 3, v0
	v_add_u32_e32 v244, s46, v244
	v_mov_b32_e32 v245, 0
	v_lshlrev_b32_e32 v244, 3, v244
	v_readlane_b32 s98, v253, 18
	v_readlane_b32 s99, v253, 19
	s_nop 1
	v_lshl_add_u64 v[240:241], s[98:99], 0, v[246:247]
	v_readlane_b32 s98, v253, 20
	v_readlane_b32 s99, v253, 21
	s_nop 1
	v_lshl_add_u64 v[242:243], s[98:99], 0, v[246:247]
	s_add_u32 s98, s62, 0xf000000
	s_addc_u32 s99, s63, 0
	v_lshl_add_u64 v[238:239], s[98:99], 0, v[244:245]
	v_ashrrev_i32_e32 v146, 3, v148
	v_lshlrev_b32_e32 v162, 3, v148
	v_add_u32_e32 v132, s46, v146
	v_bfe_u32 v149, v148, 4, 2
	v_and_b32_e32 v180, 56, v162
	v_lshrrev_b32_e32 v130, 1, v148
	v_ashrrev_i32_e32 v133, 31, v132
	v_and_b32_e32 v138, 15, v148
	v_and_b32_e32 v158, 0x60, v130
	v_lshlrev_b32_e32 v160, 4, v149
	v_lshl_or_b32 v130, s75, 7, v180
	v_lshlrev_b64 v[132:133], 12, v[132:133]
	v_lshlrev_b32_e32 v148, 7, v148
	v_or_b32_e32 v159, v158, v138
	v_ashrrev_i32_e32 v131, 31, v130
	v_lshl_add_u64 v[142:143], s[66:67], 0, v[132:133]
	v_bitop3_b32 v138, v158, v160, v138 bitop3:0x36
	v_and_b32_e32 v148, 0xffff8000, v148
	v_lshlrev_b64 v[140:141], 2, v[130:131]
	v_lshl_add_u64 v[144:145], v[142:143], 0, s[40:41]
	v_lshlrev_b32_e32 v138, 2, v138
	v_lshl_or_b32 v148, v149, 11, v148
	v_lshl_add_u64 v[178:179], v[142:143], 0, v[140:141]
	v_lshl_add_u64 v[134:135], v[144:145], 0, v[140:141]
	v_add3_u32 v138, s43, v138, v148
	global_load_dwordx2 v[194:195], v[238:239], off offset:0
	global_load_dwordx2 v[196:197], v[238:239], off offset:512
	global_load_dwordx4 v[202:205], v[240:241], off offset:0
	global_load_dwordx4 v[206:209], v[240:241], off offset:16
	global_load_dwordx4 v[210:213], v[242:243], off offset:0
	global_load_dwordx4 v[214:217], v[242:243], off offset:16
	global_load_dwordx4 v[150:153], v[178:179], off offset:16
	global_load_dwordx4 v[154:157], v[178:179], off
	global_load_dwordx4 v[130:133], v[134:135], off offset:16
	s_nop 0
	global_load_dwordx4 v[134:137], v[134:135], off
	ds_write2st64_b32 v138, v126, v127 offset1:2
	ds_write2st64_b32 v138, v128, v129 offset0:4 offset1:6
	v_bitop3_b32 v126, v159, v160, 16 bitop3:0x36
	v_lshlrev_b32_e32 v126, 2, v126
	v_readlane_b32 s76, v253, 32
	v_add3_u32 v126, s43, v126, v148
	v_readlane_b32 s88, v253, 44
	v_readlane_b32 s89, v253, 45
	ds_write2st64_b32 v126, v98, v99 offset1:2
	ds_write2st64_b32 v126, v100, v101 offset0:4 offset1:6
	ds_write2st64_b32 v138, v102, v103 offset0:32 offset1:34
	ds_write2st64_b32 v138, v104, v105 offset0:36 offset1:38
	ds_write2st64_b32 v126, v106, v107 offset0:32 offset1:34
	ds_write2st64_b32 v126, v108, v109 offset0:36 offset1:38
	ds_write2st64_b32 v138, v110, v111 offset0:64 offset1:66
	ds_write2st64_b32 v138, v112, v113 offset0:68 offset1:70
	ds_write2st64_b32 v126, v114, v115 offset0:64 offset1:66
	ds_write2st64_b32 v126, v116, v117 offset0:68 offset1:70
	ds_write2st64_b32 v138, v118, v119 offset0:96 offset1:98
	ds_write2st64_b32 v138, v120, v121 offset0:100 offset1:102
	ds_write2st64_b32 v126, v122, v123 offset0:96 offset1:98
	ds_write2st64_b32 v126, v124, v125 offset0:100 offset1:102
	v_lshl_add_u64 v[98:99], s[88:89], 0, v[140:141]
	s_waitcnt lgkmcnt(0)
	s_barrier
	global_load_dwordx4 v[112:115], v[98:99], off
	global_load_dwordx4 v[116:119], v[98:99], off offset:16
	v_readlane_b32 s84, v253, 40
	v_readlane_b32 s85, v253, 41
	v_lshlrev_b32_e32 v104, 2, v146
	v_and_b32_e32 v102, 0x60, v147
	v_lshl_add_u64 v[100:101], s[84:85], 0, v[140:141]
	global_load_dwordx4 v[120:123], v[100:101], off
	global_load_dwordx4 v[158:161], v[100:101], off offset:16
	v_and_b32_e32 v103, 8, v162
	v_and_b32_e32 v104, 48, v104
	v_bitop3_b32 v105, v102, v104, v103 bitop3:0x36
	v_or_b32_e32 v107, v102, v103
	v_lshlrev_b32_e32 v105, 2, v105
	v_lshlrev_b32_e32 v106, 9, v146
	v_add3_u32 v108, s43, v105, v106
	v_bitop3_b32 v105, v107, v104, 4 bitop3:0x36
	v_lshlrev_b32_e32 v105, 2, v105
	v_add3_u32 v109, s43, v105, v106
	v_bitop3_b32 v105, v107, v104, 16 bitop3:0x36
	v_bitop3_b32 v104, v107, v104, 20 bitop3:0x36
	v_lshlrev_b32_e32 v104, 2, v104
	v_add_u32_e32 v127, 64, v146
	v_add3_u32 v111, s43, v104, v106
	v_lshlrev_b32_e32 v104, 2, v127
	v_lshlrev_b32_e32 v105, 2, v105
	v_and_b32_e32 v124, 48, v104
	v_add3_u32 v110, s43, v105, v106
	v_bitop3_b32 v102, v102, v124, v103 bitop3:0x36
	v_lshlrev_b32_e32 v102, 2, v102
	v_lshlrev_b32_e32 v103, 9, v127
	ds_read_b128 v[162:165], v110
	ds_read_b128 v[166:169], v111
	v_add3_u32 v104, s43, v102, v103
	v_bitop3_b32 v102, v107, v124, 4 bitop3:0x36
	v_lshlrev_b32_e32 v102, 2, v102
	v_add3_u32 v105, s43, v102, v103
	v_bitop3_b32 v102, v107, v124, 16 bitop3:0x36
	v_lshlrev_b32_e32 v102, 2, v102
	v_add3_u32 v106, s43, v102, v103
	v_bitop3_b32 v102, v107, v124, 20 bitop3:0x36
	v_lshlrev_b32_e32 v102, 2, v102
	ds_read_b128 v[170:173], v108
	ds_read_b128 v[174:177], v109
	s_ashr_i32 s0, s0, 1
	v_readlane_b32 s86, v253, 42
	v_readlane_b32 s87, v253, 43
	v_readlane_b32 s90, v253, 46
	v_readlane_b32 s91, v253, 47
	v_readlane_b32 s90, v254, 44
	v_readlane_b32 s86, v254, 38
	s_mov_b64 s[70:71], 0
	s_andn2_b64 vcc, exec, s[44:45]
	v_readlane_b32 s91, v254, 45
	v_readlane_b32 s87, v254, 39
	v_readlane_b32 s77, v253, 33
	v_readlane_b32 s78, v253, 34
	v_readlane_b32 s79, v253, 35
	v_readlane_b32 s80, v253, 36
	v_readlane_b32 s81, v253, 37
	v_readlane_b32 s82, v253, 38
	v_readlane_b32 s83, v253, 39
	s_waitcnt vmcnt(0) lgkmcnt(0)
	v_add_f32_e32 v107, v112, v162
	v_mul_f32_e32 v107, 0xbfb8aa3b, v107
	v_exp_f32_e32 v124, v107
	v_add3_u32 v107, s43, v102, v103
	v_add_f32_e32 v103, v116, v166
	v_add_f32_e32 v129, v118, v168
	v_add_f32_e32 v102, 1.0, v124
	v_mul_f32_e32 v103, 0xbfb8aa3b, v103
	v_add_f32_e32 v124, v113, v163
	v_add_f32_e32 v128, v114, v164
	v_mul_f32_e32 v129, 0xbfb8aa3b, v129
	v_add_f32_e32 v147, v115, v165
	v_exp_f32_e32 v103, v103
	v_mul_f32_e32 v124, 0xbfb8aa3b, v124
	v_mul_f32_e32 v128, 0xbfb8aa3b, v128
	v_exp_f32_e32 v129, v129
	v_mul_f32_e32 v147, 0xbfb8aa3b, v147
	v_exp_f32_e32 v125, v124
	v_exp_f32_e32 v128, v128
	v_exp_f32_e32 v147, v147
	v_add_f32_e32 v103, 1.0, v103
	v_add_f32_e32 v129, 1.0, v129
	v_rcp_f32_e32 v124, v103
	v_add_f32_e32 v103, 1.0, v125
	v_add_f32_e32 v125, v117, v167
	v_add_f32_e32 v128, 1.0, v128
	v_rcp_f32_e32 v148, v129
	v_add_f32_e32 v129, 1.0, v147
	v_add_f32_e32 v147, v119, v169
	v_mul_f32_e32 v125, 0xbfb8aa3b, v125
	v_rcp_f32_e32 v128, v128
	v_rcp_f32_e32 v129, v129
	v_mul_f32_e32 v147, 0xbfb8aa3b, v147
	v_exp_f32_e32 v125, v125
	v_exp_f32_e32 v147, v147
	v_pk_add_f32 v[162:163], v[122:123], v[172:173]
	v_rcp_f32_e32 v102, v102
	v_rcp_f32_e32 v103, v103
	v_pk_mul_f32 v[128:129], v[162:163], v[128:129]
	v_add_f32_e32 v125, 1.0, v125
	v_pk_add_f32 v[156:157], v[156:157], v[194:195] op_sel_hi:[1,0] neg_lo:[0,1] neg_hi:[0,1]
	v_pk_mul_f32 v[156:157], v[156:157], v[194:195] op_sel:[0,1]
	v_pk_fma_f32 v[156:157], v[204:205], v[156:157], v[212:213]
	v_pk_fma_f32 v[156:157], v[156:157], s[42:43], v[128:129] op_sel_hi:[1,0,1]
	v_add_f32_e32 v128, 1.0, v147
	v_rcp_f32_e32 v125, v125
	v_rcp_f32_e32 v149, v128
	v_pk_add_f32 v[164:165], v[120:121], v[170:171]
	v_pk_add_f32 v[128:129], v[158:159], v[174:175]
	v_pk_mul_f32 v[102:103], v[164:165], v[102:103]
	v_pk_mul_f32 v[124:125], v[128:129], v[124:125]
	v_pk_add_f32 v[154:155], v[154:155], v[194:195] op_sel_hi:[1,0] neg_lo:[0,1] neg_hi:[0,1]
	v_pk_mul_f32 v[154:155], v[154:155], v[194:195] op_sel:[0,1]
	v_pk_fma_f32 v[154:155], v[202:203], v[154:155], v[210:211]
	v_pk_fma_f32 v[154:155], v[154:155], s[42:43], v[102:103] op_sel_hi:[1,0,1]
	v_pk_add_f32 v[102:103], v[160:161], v[176:177]
	ds_read_b128 v[162:165], v106
	v_pk_mul_f32 v[102:103], v[102:103], v[148:149]
	v_pk_add_f32 v[150:151], v[150:151], v[194:195] op_sel_hi:[1,0] neg_lo:[0,1] neg_hi:[0,1]
	v_pk_mul_f32 v[150:151], v[150:151], v[194:195] op_sel:[0,1]
	v_pk_fma_f32 v[150:151], v[206:207], v[150:151], v[214:215]
	v_pk_fma_f32 v[150:151], v[150:151], s[42:43], v[124:125] op_sel_hi:[1,0,1]
	v_pk_add_f32 v[152:153], v[152:153], v[194:195] op_sel_hi:[1,0] neg_lo:[0,1] neg_hi:[0,1]
	v_pk_mul_f32 v[152:153], v[152:153], v[194:195] op_sel:[0,1]
	v_pk_fma_f32 v[152:153], v[208:209], v[152:153], v[216:217]
	v_pk_fma_f32 v[152:153], v[152:153], s[42:43], v[102:103] op_sel_hi:[1,0,1]
	global_store_dwordx4 v[178:179], v[154:157], off
	global_store_dwordx4 v[178:179], v[150:153], off offset:16
	ds_read_b128 v[148:151], v107
	s_waitcnt lgkmcnt(1)
	v_add_f32_e32 v102, v112, v162
	v_add_f32_e32 v113, v113, v163
	v_add_f32_e32 v114, v114, v164
	v_add_f32_e32 v115, v115, v165
	v_mul_f32_e32 v102, 0xbfb8aa3b, v102
	s_waitcnt lgkmcnt(0)
	v_add_f32_e32 v116, v116, v148
	v_mul_f32_e32 v113, 0xbfb8aa3b, v113
	v_add_f32_e32 v117, v117, v149
	v_mul_f32_e32 v114, 0xbfb8aa3b, v114
	v_add_f32_e32 v118, v118, v150
	v_mul_f32_e32 v115, 0xbfb8aa3b, v115
	v_add_f32_e32 v119, v119, v151
	v_exp_f32_e32 v112, v102
	v_mul_f32_e32 v116, 0xbfb8aa3b, v116
	v_exp_f32_e32 v113, v113
	v_mul_f32_e32 v117, 0xbfb8aa3b, v117
	v_exp_f32_e32 v114, v114
	v_mul_f32_e32 v118, 0xbfb8aa3b, v118
	v_exp_f32_e32 v115, v115
	v_mul_f32_e32 v119, 0xbfb8aa3b, v119
	v_exp_f32_e32 v116, v116
	v_exp_f32_e32 v117, v117
	v_exp_f32_e32 v118, v118
	v_exp_f32_e32 v119, v119
	ds_read_b128 v[152:155], v104
	ds_read_b128 v[166:169], v105
	v_add_f32_e32 v112, 1.0, v112
	v_add_f32_e32 v113, 1.0, v113
	v_add_f32_e32 v114, 1.0, v114
	v_add_f32_e32 v115, 1.0, v115
	v_rcp_f32_e32 v112, v112
	v_add_f32_e32 v116, 1.0, v116
	v_rcp_f32_e32 v113, v113
	v_add_f32_e32 v117, 1.0, v117
	v_rcp_f32_e32 v114, v114
	v_add_f32_e32 v118, 1.0, v118
	v_rcp_f32_e32 v115, v115
	v_add_f32_e32 v119, 1.0, v119
	v_add_u32_e32 v102, s46, v127
	v_rcp_f32_e32 v116, v116
	v_rcp_f32_e32 v117, v117
	v_rcp_f32_e32 v118, v118
	v_rcp_f32_e32 v119, v119
	v_ashrrev_i32_e32 v103, 31, v102
	s_waitcnt lgkmcnt(1)
	v_pk_add_f32 v[122:123], v[122:123], v[154:155]
	v_pk_add_f32 v[120:121], v[120:121], v[152:153]
	v_lshlrev_b64 v[102:103], 12, v[102:103]
	v_pk_mul_f32 v[114:115], v[122:123], v[114:115]
	v_pk_mul_f32 v[112:113], v[120:121], v[112:113]
	s_waitcnt lgkmcnt(0)
	v_pk_add_f32 v[120:121], v[160:161], v[168:169]
	v_pk_add_f32 v[122:123], v[158:159], v[166:167]
	v_lshl_add_u64 v[102:103], s[66:67], 0, v[102:103]
	v_pk_add_f32 v[136:137], v[136:137], v[196:197] op_sel_hi:[1,0] neg_lo:[0,1] neg_hi:[0,1]
	v_pk_mul_f32 v[136:137], v[136:137], v[196:197] op_sel:[0,1]
	v_pk_fma_f32 v[136:137], v[204:205], v[136:137], v[212:213]
	v_pk_fma_f32 v[114:115], v[136:137], s[42:43], v[114:115] op_sel_hi:[1,0,1]
	v_pk_add_f32 v[134:135], v[134:135], v[196:197] op_sel_hi:[1,0] neg_lo:[0,1] neg_hi:[0,1]
	v_pk_mul_f32 v[134:135], v[134:135], v[196:197] op_sel:[0,1]
	v_pk_fma_f32 v[134:135], v[202:203], v[134:135], v[210:211]
	v_pk_fma_f32 v[112:113], v[134:135], s[42:43], v[112:113] op_sel_hi:[1,0,1]
	v_pk_mul_f32 v[118:119], v[120:121], v[118:119]
	v_pk_mul_f32 v[116:117], v[122:123], v[116:117]
	v_lshl_add_u64 v[102:103], v[102:103], 0, v[140:141]
	v_pk_add_f32 v[132:133], v[132:133], v[196:197] op_sel_hi:[1,0] neg_lo:[0,1] neg_hi:[0,1]
	v_pk_mul_f32 v[132:133], v[132:133], v[196:197] op_sel:[0,1]
	v_pk_fma_f32 v[132:133], v[208:209], v[132:133], v[216:217]
	v_pk_fma_f32 v[118:119], v[132:133], s[42:43], v[118:119] op_sel_hi:[1,0,1]
	v_pk_add_f32 v[130:131], v[130:131], v[196:197] op_sel_hi:[1,0] neg_lo:[0,1] neg_hi:[0,1]
	v_pk_mul_f32 v[130:131], v[130:131], v[196:197] op_sel:[0,1]
	v_pk_fma_f32 v[130:131], v[206:207], v[130:131], v[214:215]
	v_pk_fma_f32 v[116:117], v[130:131], s[42:43], v[116:117] op_sel_hi:[1,0,1]
	global_store_dwordx4 v[102:103], v[112:115], off
	global_store_dwordx4 v[102:103], v[116:119], off offset:16
	v_or_b32_e32 v102, s0, v180
	v_ashrrev_i32_e32 v103, 31, v102
	v_lshlrev_b64 v[102:103], 2, v[102:103]
	v_lshl_add_u64 v[124:125], v[142:143], 0, v[102:103]
	v_lshl_add_u64 v[136:137], v[144:145], 0, v[102:103]
	s_waitcnt lgkmcnt(0)
	s_barrier
	global_load_dwordx2 v[194:195], v[238:239], off offset:0
	global_load_dwordx2 v[196:197], v[238:239], off offset:512
	global_load_dwordx4 v[202:205], v[240:241], off offset:256
	global_load_dwordx4 v[206:209], v[240:241], off offset:272
	global_load_dwordx4 v[210:213], v[242:243], off offset:256
	global_load_dwordx4 v[214:217], v[242:243], off offset:272
	global_load_dwordx4 v[112:115], v[124:125], off offset:16
	global_load_dwordx4 v[116:119], v[124:125], off
	global_load_dwordx4 v[120:123], v[136:137], off offset:16
	global_load_dwordx4 v[128:131], v[136:137], off
	ds_write2st64_b32 v138, v66, v67 offset1:2
	ds_write2st64_b32 v138, v68, v69 offset0:4 offset1:6
	ds_write2st64_b32 v126, v70, v71 offset1:2
	ds_write2st64_b32 v126, v72, v73 offset0:4 offset1:6
	ds_write2st64_b32 v138, v74, v75 offset0:32 offset1:34
	ds_write2st64_b32 v138, v76, v77 offset0:36 offset1:38
	ds_write2st64_b32 v126, v78, v79 offset0:32 offset1:34
	ds_write2st64_b32 v126, v80, v81 offset0:36 offset1:38
	ds_write2st64_b32 v138, v82, v83 offset0:64 offset1:66
	ds_write2st64_b32 v138, v84, v85 offset0:68 offset1:70
	ds_write2st64_b32 v126, v86, v87 offset0:64 offset1:66
	ds_write2st64_b32 v126, v88, v89 offset0:68 offset1:70
	ds_write2st64_b32 v138, v90, v91 offset0:96 offset1:98
	ds_write2st64_b32 v138, v92, v93 offset0:100 offset1:102
	ds_write2st64_b32 v126, v94, v95 offset0:96 offset1:98
	ds_write2st64_b32 v126, v96, v97 offset0:100 offset1:102
	v_lshl_add_u64 v[66:67], s[88:89], 0, v[102:103]
	s_waitcnt lgkmcnt(0)
	s_barrier
	global_load_dwordx4 v[70:73], v[66:67], off
	global_load_dwordx4 v[74:77], v[66:67], off offset:16
	v_lshl_add_u64 v[68:69], s[84:85], 0, v[102:103]
	global_load_dwordx4 v[78:81], v[68:69], off
	global_load_dwordx4 v[82:85], v[68:69], off offset:16
	ds_read_b128 v[86:89], v110
	ds_read_b128 v[90:93], v111
	ds_read_b128 v[94:97], v108
	ds_read_b128 v[132:135], v109
	v_readlane_b32 s84, v254, 40
	s_mov_b32 s0, s74
	v_readlane_b32 s85, v254, 41
	s_waitcnt vmcnt(3) lgkmcnt(3)
	v_add_f32_e32 v86, v70, v86
	v_add_f32_e32 v87, v71, v87
	v_add_f32_e32 v88, v72, v88
	v_add_f32_e32 v89, v73, v89
	v_mul_f32_e32 v86, 0xbfb8aa3b, v86
	s_waitcnt vmcnt(2) lgkmcnt(2)
	v_add_f32_e32 v90, v74, v90
	v_mul_f32_e32 v87, 0xbfb8aa3b, v87
	v_add_f32_e32 v91, v75, v91
	v_mul_f32_e32 v88, 0xbfb8aa3b, v88
	v_add_f32_e32 v92, v76, v92
	v_mul_f32_e32 v89, 0xbfb8aa3b, v89
	v_add_f32_e32 v93, v77, v93
	v_exp_f32_e32 v86, v86
	v_mul_f32_e32 v90, 0xbfb8aa3b, v90
	v_exp_f32_e32 v87, v87
	v_mul_f32_e32 v91, 0xbfb8aa3b, v91
	v_exp_f32_e32 v88, v88
	v_mul_f32_e32 v92, 0xbfb8aa3b, v92
	v_exp_f32_e32 v89, v89
	v_mul_f32_e32 v93, 0xbfb8aa3b, v93
	v_exp_f32_e32 v90, v90
	v_exp_f32_e32 v91, v91
	v_exp_f32_e32 v92, v92
	v_exp_f32_e32 v93, v93
	v_add_f32_e32 v86, 1.0, v86
	v_add_f32_e32 v87, 1.0, v87
	v_add_f32_e32 v88, 1.0, v88
	v_add_f32_e32 v89, 1.0, v89
	v_rcp_f32_e32 v86, v86
	v_add_f32_e32 v90, 1.0, v90
	v_rcp_f32_e32 v87, v87
	v_add_f32_e32 v91, 1.0, v91
	v_rcp_f32_e32 v88, v88
	v_add_f32_e32 v92, 1.0, v92
	v_rcp_f32_e32 v89, v89
	v_add_f32_e32 v93, 1.0, v93
	v_rcp_f32_e32 v90, v90
	v_rcp_f32_e32 v91, v91
	v_rcp_f32_e32 v92, v92
	v_rcp_f32_e32 v93, v93
	s_waitcnt vmcnt(1) lgkmcnt(1)
	v_pk_add_f32 v[96:97], v[80:81], v[96:97]
	v_pk_add_f32 v[94:95], v[78:79], v[94:95]
	v_pk_mul_f32 v[88:89], v[96:97], v[88:89]
	v_pk_mul_f32 v[86:87], v[94:95], v[86:87]
	s_waitcnt vmcnt(0) lgkmcnt(0)
	v_pk_add_f32 v[94:95], v[84:85], v[134:135]
	v_pk_add_f32 v[96:97], v[82:83], v[132:133]
	v_pk_add_f32 v[118:119], v[118:119], v[194:195] op_sel_hi:[1,0] neg_lo:[0,1] neg_hi:[0,1]
	v_pk_mul_f32 v[118:119], v[118:119], v[194:195] op_sel:[0,1]
	v_pk_fma_f32 v[118:119], v[204:205], v[118:119], v[212:213]
	v_pk_fma_f32 v[88:89], v[118:119], s[42:43], v[88:89] op_sel_hi:[1,0,1]
	v_pk_add_f32 v[116:117], v[116:117], v[194:195] op_sel_hi:[1,0] neg_lo:[0,1] neg_hi:[0,1]
	v_pk_mul_f32 v[116:117], v[116:117], v[194:195] op_sel:[0,1]
	v_pk_fma_f32 v[116:117], v[202:203], v[116:117], v[210:211]
	v_pk_fma_f32 v[86:87], v[116:117], s[42:43], v[86:87] op_sel_hi:[1,0,1]
	v_pk_mul_f32 v[94:95], v[94:95], v[92:93]
	v_pk_mul_f32 v[116:117], v[96:97], v[90:91]
	ds_read_b128 v[90:93], v106
	global_store_dwordx4 v[124:125], v[86:89], off
	ds_read_b128 v[86:89], v107
	v_pk_add_f32 v[114:115], v[114:115], v[194:195] op_sel_hi:[1,0] neg_lo:[0,1] neg_hi:[0,1]
	v_pk_mul_f32 v[114:115], v[114:115], v[194:195] op_sel:[0,1]
	v_pk_fma_f32 v[114:115], v[208:209], v[114:115], v[216:217]
	v_pk_fma_f32 v[96:97], v[114:115], s[42:43], v[94:95] op_sel_hi:[1,0,1]
	v_pk_add_f32 v[112:113], v[112:113], v[194:195] op_sel_hi:[1,0] neg_lo:[0,1] neg_hi:[0,1]
	v_pk_mul_f32 v[112:113], v[112:113], v[194:195] op_sel:[0,1]
	v_pk_fma_f32 v[112:113], v[206:207], v[112:113], v[214:215]
	v_pk_fma_f32 v[94:95], v[112:113], s[42:43], v[116:117] op_sel_hi:[1,0,1]
	s_waitcnt lgkmcnt(1)
	v_add_f32_e32 v70, v70, v90
	v_add_f32_e32 v71, v71, v91
	v_add_f32_e32 v72, v72, v92
	v_add_f32_e32 v73, v73, v93
	v_mul_f32_e32 v70, 0xbfb8aa3b, v70
	s_waitcnt lgkmcnt(0)
	v_add_f32_e32 v74, v74, v86
	v_mul_f32_e32 v71, 0xbfb8aa3b, v71
	v_add_f32_e32 v75, v75, v87
	v_mul_f32_e32 v72, 0xbfb8aa3b, v72
	v_add_f32_e32 v76, v76, v88
	v_mul_f32_e32 v73, 0xbfb8aa3b, v73
	v_add_f32_e32 v77, v77, v89
	v_exp_f32_e32 v70, v70
	v_mul_f32_e32 v74, 0xbfb8aa3b, v74
	v_exp_f32_e32 v71, v71
	v_mul_f32_e32 v75, 0xbfb8aa3b, v75
	v_exp_f32_e32 v72, v72
	v_mul_f32_e32 v76, 0xbfb8aa3b, v76
	v_exp_f32_e32 v73, v73
	v_mul_f32_e32 v77, 0xbfb8aa3b, v77
	v_exp_f32_e32 v74, v74
	v_exp_f32_e32 v75, v75
	v_exp_f32_e32 v76, v76
	v_exp_f32_e32 v77, v77
	global_store_dwordx4 v[124:125], v[94:97], off offset:16
	ds_read_b128 v[94:97], v104
	ds_read_b128 v[112:115], v105
	v_add_f32_e32 v70, 1.0, v70
	v_add_f32_e32 v71, 1.0, v71
	v_add_f32_e32 v72, 1.0, v72
	v_add_f32_e32 v73, 1.0, v73
	v_rcp_f32_e32 v70, v70
	v_add_f32_e32 v74, 1.0, v74
	v_rcp_f32_e32 v71, v71
	v_add_f32_e32 v75, 1.0, v75
	v_rcp_f32_e32 v72, v72
	v_add_f32_e32 v76, 1.0, v76
	v_rcp_f32_e32 v73, v73
	v_add_f32_e32 v77, 1.0, v77
	v_rcp_f32_e32 v74, v74
	v_rcp_f32_e32 v75, v75
	v_rcp_f32_e32 v76, v76
	v_rcp_f32_e32 v77, v77
	s_waitcnt lgkmcnt(1)
	v_pk_add_f32 v[80:81], v[80:81], v[96:97]
	v_pk_add_f32 v[78:79], v[78:79], v[94:95]
	v_pk_mul_f32 v[72:73], v[80:81], v[72:73]
	v_pk_mul_f32 v[70:71], v[78:79], v[70:71]
	s_waitcnt lgkmcnt(0)
	v_pk_add_f32 v[78:79], v[84:85], v[114:115]
	v_pk_add_f32 v[80:81], v[82:83], v[112:113]
	v_pk_add_f32 v[130:131], v[130:131], v[196:197] op_sel_hi:[1,0] neg_lo:[0,1] neg_hi:[0,1]
	v_pk_mul_f32 v[130:131], v[130:131], v[196:197] op_sel:[0,1]
	v_pk_fma_f32 v[130:131], v[204:205], v[130:131], v[212:213]
	v_pk_fma_f32 v[72:73], v[130:131], s[42:43], v[72:73] op_sel_hi:[1,0,1]
	v_pk_add_f32 v[128:129], v[128:129], v[196:197] op_sel_hi:[1,0] neg_lo:[0,1] neg_hi:[0,1]
	v_pk_mul_f32 v[128:129], v[128:129], v[196:197] op_sel:[0,1]
	v_pk_fma_f32 v[128:129], v[202:203], v[128:129], v[210:211]
	v_pk_fma_f32 v[70:71], v[128:129], s[42:43], v[70:71] op_sel_hi:[1,0,1]
	v_pk_mul_f32 v[76:77], v[78:79], v[76:77]
	v_pk_mul_f32 v[74:75], v[80:81], v[74:75]
	v_pk_add_f32 v[122:123], v[122:123], v[196:197] op_sel_hi:[1,0] neg_lo:[0,1] neg_hi:[0,1]
	v_pk_mul_f32 v[122:123], v[122:123], v[196:197] op_sel:[0,1]
	v_pk_fma_f32 v[122:123], v[208:209], v[122:123], v[216:217]
	v_pk_fma_f32 v[76:77], v[122:123], s[42:43], v[76:77] op_sel_hi:[1,0,1]
	v_pk_add_f32 v[120:121], v[120:121], v[196:197] op_sel_hi:[1,0] neg_lo:[0,1] neg_hi:[0,1]
	v_pk_mul_f32 v[120:121], v[120:121], v[196:197] op_sel:[0,1]
	v_pk_fma_f32 v[120:121], v[206:207], v[120:121], v[214:215]
	v_pk_fma_f32 v[74:75], v[120:121], s[42:43], v[74:75] op_sel_hi:[1,0,1]
	global_store_dwordx4 v[136:137], v[70:73], off
	global_store_dwordx4 v[136:137], v[74:77], off offset:16
	s_waitcnt lgkmcnt(0)
	s_barrier
	v_add_u32_e32 v70, s64, v146
	v_ashrrev_i32_e32 v71, 31, v70
	v_lshlrev_b64 v[70:71], 12, v[70:71]
	v_lshl_add_u64 v[86:87], s[66:67], 0, v[70:71]
	v_lshl_add_u64 v[90:91], v[86:87], 0, s[40:41]
	v_lshl_add_u64 v[88:89], v[86:87], 0, v[140:141]
	v_lshl_add_u64 v[92:93], v[90:91], 0, v[140:141]
	global_load_dwordx2 v[194:195], v[238:239], off offset:1024
	global_load_dwordx2 v[196:197], v[238:239], off offset:1536
	global_load_dwordx4 v[202:205], v[240:241], off offset:0
	global_load_dwordx4 v[206:209], v[240:241], off offset:16
	global_load_dwordx4 v[210:213], v[242:243], off offset:0
	global_load_dwordx4 v[214:217], v[242:243], off offset:16
	global_load_dwordx4 v[70:73], v[88:89], off offset:16
	global_load_dwordx4 v[74:77], v[88:89], off
	global_load_dwordx4 v[78:81], v[92:93], off offset:16
	global_load_dwordx4 v[82:85], v[92:93], off
	ds_write2st64_b32 v138, v34, v35 offset1:2
	ds_write2st64_b32 v138, v36, v37 offset0:4 offset1:6
	ds_write2st64_b32 v126, v38, v39 offset1:2
	ds_write2st64_b32 v126, v40, v41 offset0:4 offset1:6
	ds_write2st64_b32 v138, v42, v43 offset0:32 offset1:34
	ds_write2st64_b32 v138, v44, v45 offset0:36 offset1:38
	ds_write2st64_b32 v126, v46, v47 offset0:32 offset1:34
	ds_write2st64_b32 v126, v48, v49 offset0:36 offset1:38
	ds_write2st64_b32 v138, v50, v51 offset0:64 offset1:66
	ds_write2st64_b32 v138, v52, v53 offset0:68 offset1:70
	ds_write2st64_b32 v126, v54, v55 offset0:64 offset1:66
	ds_write2st64_b32 v126, v56, v57 offset0:68 offset1:70
	ds_write2st64_b32 v138, v58, v59 offset0:96 offset1:98
	ds_write2st64_b32 v138, v60, v61 offset0:100 offset1:102
	ds_write2st64_b32 v126, v62, v63 offset0:96 offset1:98
	ds_write2st64_b32 v126, v64, v65 offset0:100 offset1:102
	s_waitcnt lgkmcnt(0)
	s_barrier
	global_load_dwordx4 v[34:37], v[98:99], off
	global_load_dwordx4 v[38:41], v[98:99], off offset:16
	global_load_dwordx4 v[42:45], v[100:101], off
	global_load_dwordx4 v[46:49], v[100:101], off offset:16
	ds_read_b128 v[50:53], v110
	ds_read_b128 v[54:57], v111
	ds_read_b128 v[58:61], v108
	ds_read_b128 v[62:65], v109
	s_waitcnt vmcnt(3) lgkmcnt(3)
	v_add_f32_e32 v50, v34, v50
	v_add_f32_e32 v51, v35, v51
	v_add_f32_e32 v52, v36, v52
	v_add_f32_e32 v53, v37, v53
	v_mul_f32_e32 v50, 0xbfb8aa3b, v50
	s_waitcnt vmcnt(2) lgkmcnt(2)
	v_add_f32_e32 v54, v38, v54
	v_mul_f32_e32 v51, 0xbfb8aa3b, v51
	v_add_f32_e32 v55, v39, v55
	v_mul_f32_e32 v52, 0xbfb8aa3b, v52
	v_add_f32_e32 v56, v40, v56
	v_mul_f32_e32 v53, 0xbfb8aa3b, v53
	v_add_f32_e32 v57, v41, v57
	v_exp_f32_e32 v50, v50
	v_mul_f32_e32 v54, 0xbfb8aa3b, v54
	v_exp_f32_e32 v51, v51
	v_mul_f32_e32 v55, 0xbfb8aa3b, v55
	v_exp_f32_e32 v52, v52
	v_mul_f32_e32 v56, 0xbfb8aa3b, v56
	v_exp_f32_e32 v53, v53
	v_mul_f32_e32 v57, 0xbfb8aa3b, v57
	v_exp_f32_e32 v54, v54
	v_exp_f32_e32 v55, v55
	v_exp_f32_e32 v56, v56
	v_exp_f32_e32 v57, v57
	v_add_f32_e32 v50, 1.0, v50
	v_add_f32_e32 v51, 1.0, v51
	v_add_f32_e32 v52, 1.0, v52
	v_add_f32_e32 v53, 1.0, v53
	v_rcp_f32_e32 v50, v50
	v_add_f32_e32 v54, 1.0, v54
	v_rcp_f32_e32 v51, v51
	v_add_f32_e32 v55, 1.0, v55
	v_rcp_f32_e32 v52, v52
	v_add_f32_e32 v56, 1.0, v56
	v_rcp_f32_e32 v53, v53
	v_add_f32_e32 v57, 1.0, v57
	v_rcp_f32_e32 v54, v54
	v_rcp_f32_e32 v55, v55
	v_rcp_f32_e32 v56, v56
	v_rcp_f32_e32 v57, v57
	s_waitcnt vmcnt(1) lgkmcnt(1)
	v_pk_add_f32 v[60:61], v[44:45], v[60:61]
	v_pk_add_f32 v[58:59], v[42:43], v[58:59]
	v_pk_mul_f32 v[52:53], v[60:61], v[52:53]
	v_pk_mul_f32 v[50:51], v[58:59], v[50:51]
	s_waitcnt vmcnt(0) lgkmcnt(0)
	v_pk_add_f32 v[58:59], v[48:49], v[64:65]
	v_pk_add_f32 v[60:61], v[46:47], v[62:63]
	v_pk_add_f32 v[76:77], v[76:77], v[194:195] op_sel_hi:[1,0] neg_lo:[0,1] neg_hi:[0,1]
	v_pk_mul_f32 v[76:77], v[76:77], v[194:195] op_sel:[0,1]
	v_pk_fma_f32 v[76:77], v[204:205], v[76:77], v[212:213]
	v_pk_fma_f32 v[52:53], v[76:77], s[42:43], v[52:53] op_sel_hi:[1,0,1]
	v_pk_add_f32 v[74:75], v[74:75], v[194:195] op_sel_hi:[1,0] neg_lo:[0,1] neg_hi:[0,1]
	v_pk_mul_f32 v[74:75], v[74:75], v[194:195] op_sel:[0,1]
	v_pk_fma_f32 v[74:75], v[202:203], v[74:75], v[210:211]
	v_pk_fma_f32 v[50:51], v[74:75], s[42:43], v[50:51] op_sel_hi:[1,0,1]
	v_pk_mul_f32 v[58:59], v[58:59], v[56:57]
	v_pk_mul_f32 v[62:63], v[60:61], v[54:55]
	ds_read_b128 v[54:57], v106
	global_store_dwordx4 v[88:89], v[50:53], off
	ds_read_b128 v[50:53], v107
	v_pk_add_f32 v[72:73], v[72:73], v[194:195] op_sel_hi:[1,0] neg_lo:[0,1] neg_hi:[0,1]
	v_pk_mul_f32 v[72:73], v[72:73], v[194:195] op_sel:[0,1]
	v_pk_fma_f32 v[72:73], v[208:209], v[72:73], v[216:217]
	v_pk_fma_f32 v[60:61], v[72:73], s[42:43], v[58:59] op_sel_hi:[1,0,1]
	v_pk_add_f32 v[70:71], v[70:71], v[194:195] op_sel_hi:[1,0] neg_lo:[0,1] neg_hi:[0,1]
	v_pk_mul_f32 v[70:71], v[70:71], v[194:195] op_sel:[0,1]
	v_pk_fma_f32 v[70:71], v[206:207], v[70:71], v[214:215]
	v_pk_fma_f32 v[58:59], v[70:71], s[42:43], v[62:63] op_sel_hi:[1,0,1]
	s_waitcnt lgkmcnt(1)
	v_add_f32_e32 v34, v34, v54
	v_add_f32_e32 v35, v35, v55
	v_add_f32_e32 v36, v36, v56
	v_add_f32_e32 v37, v37, v57
	v_mul_f32_e32 v34, 0xbfb8aa3b, v34
	s_waitcnt lgkmcnt(0)
	v_add_f32_e32 v38, v38, v50
	v_mul_f32_e32 v35, 0xbfb8aa3b, v35
	v_add_f32_e32 v39, v39, v51
	v_mul_f32_e32 v36, 0xbfb8aa3b, v36
	v_add_f32_e32 v40, v40, v52
	v_mul_f32_e32 v37, 0xbfb8aa3b, v37
	v_add_f32_e32 v41, v41, v53
	v_exp_f32_e32 v34, v34
	v_mul_f32_e32 v38, 0xbfb8aa3b, v38
	v_exp_f32_e32 v35, v35
	v_mul_f32_e32 v39, 0xbfb8aa3b, v39
	v_exp_f32_e32 v36, v36
	v_mul_f32_e32 v40, 0xbfb8aa3b, v40
	v_exp_f32_e32 v37, v37
	v_mul_f32_e32 v41, 0xbfb8aa3b, v41
	v_exp_f32_e32 v38, v38
	v_exp_f32_e32 v39, v39
	v_exp_f32_e32 v40, v40
	v_exp_f32_e32 v41, v41
	global_store_dwordx4 v[88:89], v[58:61], off offset:16
	ds_read_b128 v[58:61], v104
	ds_read_b128 v[62:65], v105
	v_add_f32_e32 v34, 1.0, v34
	v_add_f32_e32 v35, 1.0, v35
	v_add_f32_e32 v36, 1.0, v36
	v_add_f32_e32 v37, 1.0, v37
	v_rcp_f32_e32 v34, v34
	v_add_f32_e32 v38, 1.0, v38
	v_rcp_f32_e32 v35, v35
	v_add_f32_e32 v39, 1.0, v39
	v_rcp_f32_e32 v36, v36
	v_add_f32_e32 v40, 1.0, v40
	v_rcp_f32_e32 v37, v37
	v_add_f32_e32 v41, 1.0, v41
	v_rcp_f32_e32 v38, v38
	v_rcp_f32_e32 v39, v39
	v_rcp_f32_e32 v40, v40
	v_rcp_f32_e32 v41, v41
	s_waitcnt lgkmcnt(1)
	v_pk_add_f32 v[44:45], v[44:45], v[60:61]
	v_pk_add_f32 v[42:43], v[42:43], v[58:59]
	v_pk_mul_f32 v[36:37], v[44:45], v[36:37]
	v_pk_mul_f32 v[34:35], v[42:43], v[34:35]
	s_waitcnt lgkmcnt(0)
	v_pk_add_f32 v[42:43], v[48:49], v[64:65]
	v_pk_add_f32 v[44:45], v[46:47], v[62:63]
	v_pk_add_f32 v[84:85], v[84:85], v[196:197] op_sel_hi:[1,0] neg_lo:[0,1] neg_hi:[0,1]
	v_pk_mul_f32 v[84:85], v[84:85], v[196:197] op_sel:[0,1]
	v_pk_fma_f32 v[84:85], v[204:205], v[84:85], v[212:213]
	v_pk_fma_f32 v[36:37], v[84:85], s[42:43], v[36:37] op_sel_hi:[1,0,1]
	v_pk_add_f32 v[82:83], v[82:83], v[196:197] op_sel_hi:[1,0] neg_lo:[0,1] neg_hi:[0,1]
	v_pk_mul_f32 v[82:83], v[82:83], v[196:197] op_sel:[0,1]
	v_pk_fma_f32 v[82:83], v[202:203], v[82:83], v[210:211]
	v_pk_fma_f32 v[34:35], v[82:83], s[42:43], v[34:35] op_sel_hi:[1,0,1]
	v_pk_mul_f32 v[40:41], v[42:43], v[40:41]
	v_pk_mul_f32 v[38:39], v[44:45], v[38:39]
	v_pk_add_f32 v[80:81], v[80:81], v[196:197] op_sel_hi:[1,0] neg_lo:[0,1] neg_hi:[0,1]
	v_pk_mul_f32 v[80:81], v[80:81], v[196:197] op_sel:[0,1]
	v_pk_fma_f32 v[80:81], v[208:209], v[80:81], v[216:217]
	v_pk_fma_f32 v[40:41], v[80:81], s[42:43], v[40:41] op_sel_hi:[1,0,1]
	v_pk_add_f32 v[78:79], v[78:79], v[196:197] op_sel_hi:[1,0] neg_lo:[0,1] neg_hi:[0,1]
	v_pk_mul_f32 v[78:79], v[78:79], v[196:197] op_sel:[0,1]
	v_pk_fma_f32 v[78:79], v[206:207], v[78:79], v[214:215]
	v_pk_fma_f32 v[38:39], v[78:79], s[42:43], v[38:39] op_sel_hi:[1,0,1]
	global_store_dwordx4 v[92:93], v[34:37], off
	global_store_dwordx4 v[92:93], v[38:41], off offset:16
	v_lshl_add_u64 v[50:51], v[86:87], 0, v[102:103]
	v_lshl_add_u64 v[52:53], v[90:91], 0, v[102:103]
	s_waitcnt lgkmcnt(0)
	s_barrier
	global_load_dwordx2 v[194:195], v[238:239], off offset:1024
	global_load_dwordx2 v[196:197], v[238:239], off offset:1536
	global_load_dwordx4 v[202:205], v[240:241], off offset:256
	global_load_dwordx4 v[206:209], v[240:241], off offset:272
	global_load_dwordx4 v[210:213], v[242:243], off offset:256
	global_load_dwordx4 v[214:217], v[242:243], off offset:272
	global_load_dwordx4 v[34:37], v[50:51], off offset:16
	global_load_dwordx4 v[38:41], v[50:51], off
	global_load_dwordx4 v[42:45], v[52:53], off offset:16
	global_load_dwordx4 v[46:49], v[52:53], off
	ds_write2st64_b32 v138, v2, v3 offset1:2
	ds_write2st64_b32 v138, v4, v5 offset0:4 offset1:6
	ds_write2st64_b32 v126, v6, v7 offset1:2
	ds_write2st64_b32 v126, v8, v9 offset0:4 offset1:6
	ds_write2st64_b32 v138, v10, v11 offset0:32 offset1:34
	ds_write2st64_b32 v138, v12, v13 offset0:36 offset1:38
	ds_write2st64_b32 v126, v14, v15 offset0:32 offset1:34
	ds_write2st64_b32 v126, v16, v17 offset0:36 offset1:38
	ds_write2st64_b32 v138, v18, v19 offset0:64 offset1:66
	ds_write2st64_b32 v138, v20, v21 offset0:68 offset1:70
	ds_write2st64_b32 v126, v22, v23 offset0:64 offset1:66
	ds_write2st64_b32 v126, v24, v25 offset0:68 offset1:70
	ds_write2st64_b32 v138, v26, v27 offset0:96 offset1:98
	ds_write2st64_b32 v138, v28, v29 offset0:100 offset1:102
	ds_write2st64_b32 v126, v30, v31 offset0:96 offset1:98
	ds_write2st64_b32 v126, v32, v33 offset0:100 offset1:102
	s_waitcnt lgkmcnt(0)
	s_barrier
	global_load_dwordx4 v[2:5], v[66:67], off
	global_load_dwordx4 v[6:9], v[66:67], off offset:16
	global_load_dwordx4 v[10:13], v[68:69], off
	global_load_dwordx4 v[14:17], v[68:69], off offset:16
	ds_read_b128 v[18:21], v110
	ds_read_b128 v[22:25], v111
	ds_read_b128 v[26:29], v108
	ds_read_b128 v[30:33], v109
	s_waitcnt vmcnt(3) lgkmcnt(3)
	v_add_f32_e32 v18, v2, v18
	v_add_f32_e32 v19, v3, v19
	v_add_f32_e32 v20, v4, v20
	v_add_f32_e32 v21, v5, v21
	v_mul_f32_e32 v18, 0xbfb8aa3b, v18
	s_waitcnt vmcnt(2) lgkmcnt(2)
	v_add_f32_e32 v22, v6, v22
	v_mul_f32_e32 v19, 0xbfb8aa3b, v19
	v_add_f32_e32 v23, v7, v23
	v_mul_f32_e32 v20, 0xbfb8aa3b, v20
	v_add_f32_e32 v24, v8, v24
	v_mul_f32_e32 v21, 0xbfb8aa3b, v21
	v_add_f32_e32 v25, v9, v25
	v_exp_f32_e32 v18, v18
	v_mul_f32_e32 v22, 0xbfb8aa3b, v22
	v_exp_f32_e32 v19, v19
	v_mul_f32_e32 v23, 0xbfb8aa3b, v23
	v_exp_f32_e32 v20, v20
	v_mul_f32_e32 v24, 0xbfb8aa3b, v24
	v_exp_f32_e32 v21, v21
	v_mul_f32_e32 v25, 0xbfb8aa3b, v25
	v_exp_f32_e32 v22, v22
	v_exp_f32_e32 v23, v23
	v_exp_f32_e32 v24, v24
	v_exp_f32_e32 v25, v25
	v_add_f32_e32 v18, 1.0, v18
	v_add_f32_e32 v19, 1.0, v19
	v_add_f32_e32 v20, 1.0, v20
	v_add_f32_e32 v21, 1.0, v21
	v_rcp_f32_e32 v18, v18
	v_add_f32_e32 v22, 1.0, v22
	v_rcp_f32_e32 v19, v19
	v_add_f32_e32 v23, 1.0, v23
	v_rcp_f32_e32 v20, v20
	v_add_f32_e32 v24, 1.0, v24
	v_rcp_f32_e32 v21, v21
	v_add_f32_e32 v25, 1.0, v25
	v_rcp_f32_e32 v22, v22
	v_rcp_f32_e32 v23, v23
	v_rcp_f32_e32 v24, v24
	v_rcp_f32_e32 v25, v25
	s_waitcnt vmcnt(1) lgkmcnt(1)
	v_pk_add_f32 v[28:29], v[12:13], v[28:29]
	v_pk_add_f32 v[26:27], v[10:11], v[26:27]
	v_pk_mul_f32 v[20:21], v[28:29], v[20:21]
	v_pk_mul_f32 v[18:19], v[26:27], v[18:19]
	s_waitcnt vmcnt(0) lgkmcnt(0)
	v_pk_add_f32 v[26:27], v[16:17], v[32:33]
	v_pk_add_f32 v[28:29], v[14:15], v[30:31]
	v_pk_add_f32 v[40:41], v[40:41], v[194:195] op_sel_hi:[1,0] neg_lo:[0,1] neg_hi:[0,1]
	v_pk_mul_f32 v[40:41], v[40:41], v[194:195] op_sel:[0,1]
	v_pk_fma_f32 v[40:41], v[204:205], v[40:41], v[212:213]
	v_pk_fma_f32 v[20:21], v[40:41], s[42:43], v[20:21] op_sel_hi:[1,0,1]
	v_pk_add_f32 v[38:39], v[38:39], v[194:195] op_sel_hi:[1,0] neg_lo:[0,1] neg_hi:[0,1]
	v_pk_mul_f32 v[38:39], v[38:39], v[194:195] op_sel:[0,1]
	v_pk_fma_f32 v[38:39], v[202:203], v[38:39], v[210:211]
	v_pk_fma_f32 v[18:19], v[38:39], s[42:43], v[18:19] op_sel_hi:[1,0,1]
	v_pk_mul_f32 v[26:27], v[26:27], v[24:25]
	v_pk_mul_f32 v[30:31], v[28:29], v[22:23]
	ds_read_b128 v[22:25], v106
	global_store_dwordx4 v[50:51], v[18:21], off
	ds_read_b128 v[18:21], v107
	v_pk_add_f32 v[36:37], v[36:37], v[194:195] op_sel_hi:[1,0] neg_lo:[0,1] neg_hi:[0,1]
	v_pk_mul_f32 v[36:37], v[36:37], v[194:195] op_sel:[0,1]
	v_pk_fma_f32 v[36:37], v[208:209], v[36:37], v[216:217]
	v_pk_fma_f32 v[28:29], v[36:37], s[42:43], v[26:27] op_sel_hi:[1,0,1]
	v_pk_add_f32 v[34:35], v[34:35], v[194:195] op_sel_hi:[1,0] neg_lo:[0,1] neg_hi:[0,1]
	v_pk_mul_f32 v[34:35], v[34:35], v[194:195] op_sel:[0,1]
	v_pk_fma_f32 v[34:35], v[206:207], v[34:35], v[214:215]
	v_pk_fma_f32 v[26:27], v[34:35], s[42:43], v[30:31] op_sel_hi:[1,0,1]
	s_waitcnt lgkmcnt(1)
	v_add_f32_e32 v2, v2, v22
	v_add_f32_e32 v3, v3, v23
	v_add_f32_e32 v4, v4, v24
	v_add_f32_e32 v5, v5, v25
	v_mul_f32_e32 v2, 0xbfb8aa3b, v2
	s_waitcnt lgkmcnt(0)
	v_add_f32_e32 v6, v6, v18
	v_mul_f32_e32 v3, 0xbfb8aa3b, v3
	v_add_f32_e32 v7, v7, v19
	v_mul_f32_e32 v4, 0xbfb8aa3b, v4
	v_add_f32_e32 v8, v8, v20
	v_mul_f32_e32 v5, 0xbfb8aa3b, v5
	v_add_f32_e32 v9, v9, v21
	v_exp_f32_e32 v2, v2
	v_mul_f32_e32 v6, 0xbfb8aa3b, v6
	v_exp_f32_e32 v3, v3
	v_mul_f32_e32 v7, 0xbfb8aa3b, v7
	v_exp_f32_e32 v4, v4
	v_mul_f32_e32 v8, 0xbfb8aa3b, v8
	v_exp_f32_e32 v5, v5
	v_mul_f32_e32 v9, 0xbfb8aa3b, v9
	v_exp_f32_e32 v6, v6
	v_exp_f32_e32 v7, v7
	v_exp_f32_e32 v8, v8
	v_exp_f32_e32 v9, v9
	global_store_dwordx4 v[50:51], v[26:29], off offset:16
	ds_read_b128 v[26:29], v104
	ds_read_b128 v[30:33], v105
	v_add_f32_e32 v2, 1.0, v2
	v_add_f32_e32 v3, 1.0, v3
	v_add_f32_e32 v4, 1.0, v4
	v_add_f32_e32 v5, 1.0, v5
	v_rcp_f32_e32 v2, v2
	v_add_f32_e32 v6, 1.0, v6
	v_rcp_f32_e32 v3, v3
	v_add_f32_e32 v7, 1.0, v7
	v_rcp_f32_e32 v4, v4
	v_add_f32_e32 v8, 1.0, v8
	v_rcp_f32_e32 v5, v5
	v_add_f32_e32 v9, 1.0, v9
	v_rcp_f32_e32 v6, v6
	v_rcp_f32_e32 v7, v7
	v_rcp_f32_e32 v8, v8
	v_rcp_f32_e32 v9, v9
	s_waitcnt lgkmcnt(1)
	v_pk_add_f32 v[12:13], v[12:13], v[28:29]
	v_pk_add_f32 v[10:11], v[10:11], v[26:27]
	v_pk_mul_f32 v[4:5], v[12:13], v[4:5]
	v_pk_mul_f32 v[2:3], v[10:11], v[2:3]
	s_waitcnt lgkmcnt(0)
	v_pk_add_f32 v[10:11], v[16:17], v[32:33]
	v_pk_add_f32 v[12:13], v[14:15], v[30:31]
	v_pk_add_f32 v[48:49], v[48:49], v[196:197] op_sel_hi:[1,0] neg_lo:[0,1] neg_hi:[0,1]
	v_pk_mul_f32 v[48:49], v[48:49], v[196:197] op_sel:[0,1]
	v_pk_fma_f32 v[48:49], v[204:205], v[48:49], v[212:213]
	v_pk_fma_f32 v[4:5], v[48:49], s[42:43], v[4:5] op_sel_hi:[1,0,1]
	v_pk_add_f32 v[46:47], v[46:47], v[196:197] op_sel_hi:[1,0] neg_lo:[0,1] neg_hi:[0,1]
	v_pk_mul_f32 v[46:47], v[46:47], v[196:197] op_sel:[0,1]
	v_pk_fma_f32 v[46:47], v[202:203], v[46:47], v[210:211]
	v_pk_fma_f32 v[2:3], v[46:47], s[42:43], v[2:3] op_sel_hi:[1,0,1]
	v_pk_mul_f32 v[8:9], v[10:11], v[8:9]
	v_pk_mul_f32 v[6:7], v[12:13], v[6:7]
	v_pk_add_f32 v[44:45], v[44:45], v[196:197] op_sel_hi:[1,0] neg_lo:[0,1] neg_hi:[0,1]
	v_pk_mul_f32 v[44:45], v[44:45], v[196:197] op_sel:[0,1]
	v_pk_fma_f32 v[44:45], v[208:209], v[44:45], v[216:217]
	v_pk_fma_f32 v[8:9], v[44:45], s[42:43], v[8:9] op_sel_hi:[1,0,1]
	v_pk_add_f32 v[42:43], v[42:43], v[196:197] op_sel_hi:[1,0] neg_lo:[0,1] neg_hi:[0,1]
	v_pk_mul_f32 v[42:43], v[42:43], v[196:197] op_sel:[0,1]
	v_pk_fma_f32 v[42:43], v[206:207], v[42:43], v[214:215]
	v_pk_fma_f32 v[6:7], v[42:43], s[42:43], v[6:7] op_sel_hi:[1,0,1]
	global_store_dwordx4 v[52:53], v[2:5], off
	global_store_dwordx4 v[52:53], v[6:9], off offset:16
	s_waitcnt lgkmcnt(0)
	s_barrier
	s_cbranch_vccz .LBB0_1787
